# adds: s_setprio toggles removed from the four GEMM K-loops (plus fnbar: no grid barrier between final norm of trunk 1 and trunk-2 prologue)
# speedup vs baseline: 1.0105x; 1.0050x over previous
; #define PG8_STAGE(bufoff, gbase, voff) do { _Pragma("unroll") for (int _i = 0; _i < 2; ++_i) \
;         __builtin_amdgcn_global_load_lds((const unsigned*)((const char*)(gbase) + (voff)[_i]), (PG8_LAS unsigned*)(lds + (bufoff) + ldsw + _i * 8192), 16, 0, 0); } while (0)
; #define PG8_LDA(dst, b, h) do { _Pragma("unroll") for (int m = 0; m < 4; ++m) _Pragma("unroll") for (int k = 0; k < 2; ++k) dst[m][k] = *(const PG8_LAS bf16x8*)(lds + PG8_SA(b, h) + aoff + m * 2048 + k * 1024); } while (0)
; #define PG8_LDB(dst, b, h) do { _Pragma("unroll") for (int n = 0; n < 2; ++n) _Pragma("unroll") for (int k = 0; k < 2; ++k) dst[n][k] = *(const PG8_LAS bf16x8*)(lds + PG8_SB(b, h) + boff + n * 2048 + k * 1024); } while (0)
; #define PG8_MMA(ai, bj, At, Bt) do { __builtin_amdgcn_s_setprio(1); _Pragma("unroll") for (int m = 0; m < 4; ++m) _Pragma("unroll") for (int n = 0; n < 2; ++n) _Pragma("unroll") for (int k = 0; k < 2; ++k) \
;         acc[ai][bj][m][n] = __builtin_amdgcn_mfma_f32_16x16x32_bf16(Bt[n][k], At[m][k], acc[ai][bj][m][n], 0, 0, 0); __builtin_amdgcn_s_setprio(0); } while (0)
; #define PG8_WAIT_V(n) asm volatile("s_waitcnt vmcnt(" #n ")" ::: "memory")
; #define PG8_WAIT_L(n) asm volatile("s_waitcnt lgkmcnt(" #n ")" ::: "memory")
; #define PG8_BAR __builtin_amdgcn_s_barrier()
; #define PG8_SCHED __builtin_amdgcn_sched_barrier(0)
; template <class Epi, class Sched, bool ALIGN_EPI = false, bool SP2 = false>
; __device__ __forceinline__ void gemm_phase(PG8_LAS unsigned char* lds, const Gemm g, const Sched& S, const Epi& E, int tid_in) {
;     ...
;             PG8_LDB(B0, 0, 0); PG8_LDB(B1, 0, 1); PG8_SCHED; PG8_LDA(At, 0, 0); PG8_STAGE(PG8_SA(1, 1), a1 + hstep, voffA);
;             PG8_WAIT_V(8); PG8_WAIT_L(0); PG8_BAR; PG8_MMA(0, 0, At, B0); PG8_MMA(0, 1, At, B1); PG8_BAR; PG8_SCHED;
;             PG8_LDA(At, 0, 1); PG8_STAGE(PG8_SB(0, 0), b2, voffB); PG8_STAGE(PG8_SB(0, 1), b2 + hstep, voffB); PG8_STAGE(PG8_SA(0, 0), a2, voffA);
;             PG8_WAIT_V(8); PG8_WAIT_L(0); PG8_BAR; PG8_MMA(1, 0, At, B0); PG8_MMA(1, 1, At, B1); PG8_BAR; PG8_SCHED;
.LBB0_151:
	s_add_i32 s36, s4, 2
	s_add_u32 s37, s0, 0x80
	s_addc_u32 s5, s1, 0
	s_add_i32 s90, 0, 0x10000
	s_cmp_eq_u32 s57, s4
	s_cselect_b32 s5, s39, s5
	s_cselect_b32 s4, s38, s37
	v_add_u32_e32 v144, s90, v151
	s_cselect_b32 s89, s45, s23
	s_cselect_b32 s88, s44, s22
	s_add_i32 s37, 0, 0x14000
	ds_read_b128 v[140:143], v144
	ds_read_b128 v[166:169], v144 offset:1024
	ds_read_b128 v[170:173], v144 offset:2048
	ds_read_b128 v[174:177], v144 offset:3072
	v_add_u32_e32 v144, s37, v151
	ds_read_b128 v[178:181], v144
	ds_read_b128 v[182:185], v144 offset:1024
	ds_read_b128 v[186:189], v144 offset:2048
	ds_read_b128 v[190:193], v144 offset:3072
	v_lshl_add_u64 v[144:145], s[0:1], 0, v[136:137]
	s_add_i32 m0, s43, 0xc000
	ds_read_b128 v[194:197], v161
	ds_read_b128 v[198:201], v161 offset:1024
	ds_read_b128 v[202:205], v161 offset:2048
	ds_read_b128 v[206:209], v161 offset:3072
	ds_read_b128 v[210:213], v161 offset:4096
	ds_read_b128 v[214:217], v161 offset:5120
	ds_read_b128 v[218:221], v161 offset:6144
	ds_read_b128 v[222:225], v161 offset:7168
	global_load_lds_dwordx4 v[144:145], off
	v_lshl_add_u64 v[144:145], s[0:1], 0, v[138:139]
	s_add_i32 m0, s43, 0xe000
	s_nop 0
	global_load_lds_dwordx4 v[144:145], off
	s_waitcnt vmcnt(8)
	s_waitcnt lgkmcnt(0)
	s_barrier
	s_waitcnt lgkmcnt(0)
	v_mfma_f32_16x16x32_bf16 v[124:127], v[140:143], v[194:197], v[124:127]
	v_mfma_f32_16x16x32_bf16 v[120:123], v[170:173], v[194:197], v[120:123]
	v_mfma_f32_16x16x32_bf16 v[108:111], v[140:143], v[202:205], v[108:111]
	v_mfma_f32_16x16x32_bf16 v[104:107], v[170:173], v[202:205], v[104:107]
	v_mfma_f32_16x16x32_bf16 v[92:95], v[140:143], v[210:213], v[92:95]
	v_mfma_f32_16x16x32_bf16 v[88:91], v[170:173], v[210:213], v[88:91]
	v_mfma_f32_16x16x32_bf16 v[76:79], v[140:143], v[218:221], v[76:79]
	v_mfma_f32_16x16x32_bf16 v[72:75], v[170:173], v[218:221], v[72:75]
	v_mfma_f32_16x16x32_bf16 v[124:127], v[166:169], v[198:201], v[124:127]
	v_mfma_f32_16x16x32_bf16 v[120:123], v[174:177], v[198:201], v[120:123]
	v_mfma_f32_16x16x32_bf16 v[108:111], v[166:169], v[206:209], v[108:111]
	v_mfma_f32_16x16x32_bf16 v[104:107], v[174:177], v[206:209], v[104:107]
	v_mfma_f32_16x16x32_bf16 v[92:95], v[166:169], v[214:217], v[92:95]
	v_mfma_f32_16x16x32_bf16 v[88:91], v[174:177], v[214:217], v[88:91]
	v_mfma_f32_16x16x32_bf16 v[76:79], v[166:169], v[222:225], v[76:79]
	v_mfma_f32_16x16x32_bf16 v[72:75], v[174:177], v[222:225], v[72:75]
	v_mfma_f32_16x16x32_bf16 v[116:119], v[178:181], v[194:197], v[116:119]
	v_mfma_f32_16x16x32_bf16 v[112:115], v[186:189], v[194:197], v[112:115]
	v_mfma_f32_16x16x32_bf16 v[100:103], v[178:181], v[202:205], v[100:103]
	v_mfma_f32_16x16x32_bf16 v[96:99], v[186:189], v[202:205], v[96:99]
	v_mfma_f32_16x16x32_bf16 v[84:87], v[178:181], v[210:213], v[84:87]
	v_mfma_f32_16x16x32_bf16 v[80:83], v[186:189], v[210:213], v[80:83]
	v_mfma_f32_16x16x32_bf16 v[68:71], v[178:181], v[218:221], v[68:71]
	v_mfma_f32_16x16x32_bf16 v[64:67], v[186:189], v[218:221], v[64:67]
	v_mfma_f32_16x16x32_bf16 v[116:119], v[182:185], v[198:201], v[116:119]
	v_mfma_f32_16x16x32_bf16 v[112:115], v[190:193], v[198:201], v[112:115]
	v_mfma_f32_16x16x32_bf16 v[100:103], v[182:185], v[206:209], v[100:103]
	v_mfma_f32_16x16x32_bf16 v[96:99], v[190:193], v[206:209], v[96:99]
	v_mfma_f32_16x16x32_bf16 v[84:87], v[182:185], v[214:217], v[84:87]
	v_mfma_f32_16x16x32_bf16 v[80:83], v[190:193], v[214:217], v[80:83]
	v_mfma_f32_16x16x32_bf16 v[68:71], v[182:185], v[222:225], v[68:71]
	v_mfma_f32_16x16x32_bf16 v[64:67], v[190:193], v[222:225], v[64:67]
	s_barrier
	s_add_i32 s90, s90, s42
	v_lshl_add_u64 v[144:145], s[88:89], 0, v[156:157]
	s_mov_b32 m0, s90
	ds_read_b128 v[194:197], v161 offset:16384
	ds_read_b128 v[198:201], v161 offset:17408
	ds_read_b128 v[202:205], v161 offset:18432
	ds_read_b128 v[206:209], v161 offset:19456
	ds_read_b128 v[210:213], v161 offset:20480
	ds_read_b128 v[214:217], v161 offset:21504
	ds_read_b128 v[218:221], v161 offset:22528
	ds_read_b128 v[222:225], v161 offset:23552
	global_load_lds_dwordx4 v[144:145], off
	s_add_i32 m0, s90, 0x2000
	v_lshl_add_u64 v[226:227], s[88:89], 0, v[128:129]
	s_add_u32 s88, s88, s8
	s_addc_u32 s89, s89, s9
	s_add_i32 s37, s37, s42
	global_load_lds_dwordx4 v[226:227], off
	v_lshl_add_u64 v[228:229], s[88:89], 0, v[156:157]
	s_mov_b32 m0, s37
	v_lshl_add_u64 v[238:239], s[88:89], 0, v[128:129]
	global_load_lds_dwordx4 v[228:229], off
	s_add_i32 m0, s37, 0x2000
	v_lshl_add_u64 v[240:241], s[4:5], 0, v[132:133]
	global_load_lds_dwordx4 v[238:239], off
	s_mov_b32 m0, s43
	v_lshl_add_u64 v[242:243], s[4:5], 0, v[130:131]
	global_load_lds_dwordx4 v[240:241], off
	s_mov_b32 m0, s46
	s_nop 0
	global_load_lds_dwordx4 v[242:243], off
	s_waitcnt vmcnt(8)
	s_waitcnt lgkmcnt(0)
	s_barrier
; #define PG8_STAGE(bufoff, gbase, voff) do { _Pragma("unroll") for (int _i = 0; _i < 2; ++_i) \
;         __builtin_amdgcn_global_load_lds((const unsigned*)((const char*)(gbase) + (voff)[_i]), (PG8_LAS unsigned*)(lds + (bufoff) + ldsw + _i * 8192), 16, 0, 0); } while (0)
; #define PG8_LDA(dst, b, h) do { _Pragma("unroll") for (int m = 0; m < 4; ++m) _Pragma("unroll") for (int k = 0; k < 2; ++k) dst[m][k] = *(const PG8_LAS bf16x8*)(lds + PG8_SA(b, h) + aoff + m * 2048 + k * 1024); } while (0)
; #define PG8_LDB(dst, b, h) do { _Pragma("unroll") for (int n = 0; n < 2; ++n) _Pragma("unroll") for (int k = 0; k < 2; ++k) dst[n][k] = *(const PG8_LAS bf16x8*)(lds + PG8_SB(b, h) + boff + n * 2048 + k * 1024); } while (0)
; #define PG8_MMA(ai, bj, At, Bt) do { __builtin_amdgcn_s_setprio(1); _Pragma("unroll") for (int m = 0; m < 4; ++m) _Pragma("unroll") for (int n = 0; n < 2; ++n) _Pragma("unroll") for (int k = 0; k < 2; ++k) \
;         acc[ai][bj][m][n] = __builtin_amdgcn_mfma_f32_16x16x32_bf16(Bt[n][k], At[m][k], acc[ai][bj][m][n], 0, 0, 0); __builtin_amdgcn_s_setprio(0); } while (0)
; #define PG8_WAIT_V(n) asm volatile("s_waitcnt vmcnt(" #n ")" ::: "memory")
; #define PG8_WAIT_L(n) asm volatile("s_waitcnt lgkmcnt(" #n ")" ::: "memory")
; #define PG8_BAR __builtin_amdgcn_s_barrier()
; #define PG8_SCHED __builtin_amdgcn_sched_barrier(0)
; template <class Epi, class Sched, bool ALIGN_EPI = false, bool SP2 = false>
; __device__ __forceinline__ void gemm_phase(PG8_LAS unsigned char* lds, const Gemm g, const Sched& S, const Epi& E, int tid_in) {
;     ...
;             PG8_WAIT_V(8); PG8_WAIT_L(0); PG8_BAR; PG8_MMA(1, 0, At, B0); PG8_MMA(1, 1, At, B1); PG8_BAR; PG8_SCHED;
;             PG8_LDB(B0, 1, 0); PG8_LDB(B1, 1, 1); PG8_SCHED; PG8_LDA(At, 1, 0); PG8_STAGE(PG8_SA(0, 1), a2 + hstep, voffA);
;             PG8_WAIT_V(8); PG8_WAIT_L(0); PG8_BAR; PG8_MMA(0, 0, At, B0); PG8_MMA(0, 1, At, B1); PG8_BAR; PG8_SCHED;
	s_waitcnt lgkmcnt(0)
	v_mfma_f32_16x16x32_bf16 v[60:63], v[140:143], v[194:197], v[60:63]
	v_mfma_f32_16x16x32_bf16 v[56:59], v[170:173], v[194:197], v[56:59]
	v_mfma_f32_16x16x32_bf16 v[44:47], v[140:143], v[202:205], v[44:47]
	v_mfma_f32_16x16x32_bf16 v[40:43], v[170:173], v[202:205], v[40:43]
	v_mfma_f32_16x16x32_bf16 v[28:31], v[140:143], v[210:213], v[28:31]
	v_mfma_f32_16x16x32_bf16 v[24:27], v[170:173], v[210:213], v[24:27]
	v_mfma_f32_16x16x32_bf16 v[12:15], v[140:143], v[218:221], v[12:15]
	v_mfma_f32_16x16x32_bf16 v[8:11], v[170:173], v[218:221], v[8:11]
	v_mfma_f32_16x16x32_bf16 v[60:63], v[166:169], v[198:201], v[60:63]
	v_mfma_f32_16x16x32_bf16 v[56:59], v[174:177], v[198:201], v[56:59]
	v_mfma_f32_16x16x32_bf16 v[44:47], v[166:169], v[206:209], v[44:47]
	v_mfma_f32_16x16x32_bf16 v[40:43], v[174:177], v[206:209], v[40:43]
	v_mfma_f32_16x16x32_bf16 v[28:31], v[166:169], v[214:217], v[28:31]
	v_mfma_f32_16x16x32_bf16 v[24:27], v[174:177], v[214:217], v[24:27]
	v_mfma_f32_16x16x32_bf16 v[12:15], v[166:169], v[222:225], v[12:15]
	v_mfma_f32_16x16x32_bf16 v[8:11], v[174:177], v[222:225], v[8:11]
	v_mfma_f32_16x16x32_bf16 v[52:55], v[178:181], v[194:197], v[52:55]
	v_mfma_f32_16x16x32_bf16 v[48:51], v[186:189], v[194:197], v[48:51]
	v_mfma_f32_16x16x32_bf16 v[36:39], v[178:181], v[202:205], v[36:39]
	v_mfma_f32_16x16x32_bf16 v[32:35], v[186:189], v[202:205], v[32:35]
	v_mfma_f32_16x16x32_bf16 v[20:23], v[178:181], v[210:213], v[20:23]
	v_mfma_f32_16x16x32_bf16 v[16:19], v[186:189], v[210:213], v[16:19]
	v_mfma_f32_16x16x32_bf16 v[4:7], v[178:181], v[218:221], v[4:7]
	v_mfma_f32_16x16x32_bf16 v[0:3], v[186:189], v[218:221], v[0:3]
	v_mfma_f32_16x16x32_bf16 v[52:55], v[182:185], v[198:201], v[52:55]
	v_mfma_f32_16x16x32_bf16 v[48:51], v[190:193], v[198:201], v[48:51]
	v_mfma_f32_16x16x32_bf16 v[36:39], v[182:185], v[206:209], v[36:39]
	v_mfma_f32_16x16x32_bf16 v[32:35], v[190:193], v[206:209], v[32:35]
	v_mfma_f32_16x16x32_bf16 v[20:23], v[182:185], v[214:217], v[20:23]
	v_mfma_f32_16x16x32_bf16 v[16:19], v[190:193], v[214:217], v[16:19]
	v_mfma_f32_16x16x32_bf16 v[4:7], v[182:185], v[222:225], v[4:7]
	v_mfma_f32_16x16x32_bf16 v[0:3], v[190:193], v[222:225], v[0:3]
	s_barrier
	s_add_i32 s37, 0, 0x18000
	v_add_u32_e32 v146, s37, v151
	s_add_i32 s88, 0, 0x1c000
	ds_read_b128 v[140:143], v146
	ds_read_b128 v[166:169], v146 offset:1024
	ds_read_b128 v[170:173], v146 offset:2048
	ds_read_b128 v[174:177], v146 offset:3072
	v_add_u32_e32 v146, s88, v151
	ds_read_b128 v[178:181], v146
	ds_read_b128 v[182:185], v146 offset:1024
	ds_read_b128 v[186:189], v146 offset:2048
	ds_read_b128 v[190:193], v146 offset:3072
	s_add_u32 s4, s4, s8
	s_addc_u32 s5, s5, s9
	s_mov_b32 m0, s47
	v_lshl_add_u64 v[244:245], s[4:5], 0, v[132:133]
	ds_read_b128 v[194:197], v161 offset:32768
	ds_read_b128 v[198:201], v161 offset:33792
	ds_read_b128 v[202:205], v161 offset:34816
	ds_read_b128 v[206:209], v161 offset:35840
	ds_read_b128 v[210:213], v161 offset:36864
	ds_read_b128 v[214:217], v161 offset:37888
	ds_read_b128 v[218:221], v161 offset:38912
	ds_read_b128 v[222:225], v161 offset:39936
	global_load_lds_dwordx4 v[244:245], off
	v_lshl_add_u64 v[244:245], s[4:5], 0, v[130:131]
	s_mov_b32 m0, s52
	s_nop 0
	global_load_lds_dwordx4 v[244:245], off
	s_waitcnt vmcnt(8)
	s_waitcnt lgkmcnt(0)
	s_barrier
	s_waitcnt lgkmcnt(0)
	v_mfma_f32_16x16x32_bf16 v[124:127], v[140:143], v[194:197], v[124:127]
	v_mfma_f32_16x16x32_bf16 v[120:123], v[170:173], v[194:197], v[120:123]
	v_mfma_f32_16x16x32_bf16 v[108:111], v[140:143], v[202:205], v[108:111]
	v_mfma_f32_16x16x32_bf16 v[104:107], v[170:173], v[202:205], v[104:107]
	v_mfma_f32_16x16x32_bf16 v[92:95], v[140:143], v[210:213], v[92:95]
	v_mfma_f32_16x16x32_bf16 v[88:91], v[170:173], v[210:213], v[88:91]
	v_mfma_f32_16x16x32_bf16 v[76:79], v[140:143], v[218:221], v[76:79]
	v_mfma_f32_16x16x32_bf16 v[72:75], v[170:173], v[218:221], v[72:75]
	v_mfma_f32_16x16x32_bf16 v[124:127], v[166:169], v[198:201], v[124:127]
	v_mfma_f32_16x16x32_bf16 v[120:123], v[174:177], v[198:201], v[120:123]
	v_mfma_f32_16x16x32_bf16 v[108:111], v[166:169], v[206:209], v[108:111]
	v_mfma_f32_16x16x32_bf16 v[104:107], v[174:177], v[206:209], v[104:107]
	v_mfma_f32_16x16x32_bf16 v[92:95], v[166:169], v[214:217], v[92:95]
	v_mfma_f32_16x16x32_bf16 v[88:91], v[174:177], v[214:217], v[88:91]
	v_mfma_f32_16x16x32_bf16 v[76:79], v[166:169], v[222:225], v[76:79]
	v_mfma_f32_16x16x32_bf16 v[72:75], v[174:177], v[222:225], v[72:75]
	v_mfma_f32_16x16x32_bf16 v[116:119], v[178:181], v[194:197], v[116:119]
	v_mfma_f32_16x16x32_bf16 v[112:115], v[186:189], v[194:197], v[112:115]
	v_mfma_f32_16x16x32_bf16 v[100:103], v[178:181], v[202:205], v[100:103]
	v_mfma_f32_16x16x32_bf16 v[96:99], v[186:189], v[202:205], v[96:99]
	v_mfma_f32_16x16x32_bf16 v[84:87], v[178:181], v[210:213], v[84:87]
	v_mfma_f32_16x16x32_bf16 v[80:83], v[186:189], v[210:213], v[80:83]
	v_mfma_f32_16x16x32_bf16 v[68:71], v[178:181], v[218:221], v[68:71]
	v_mfma_f32_16x16x32_bf16 v[64:67], v[186:189], v[218:221], v[64:67]
	v_mfma_f32_16x16x32_bf16 v[116:119], v[182:185], v[198:201], v[116:119]
	v_mfma_f32_16x16x32_bf16 v[112:115], v[190:193], v[198:201], v[112:115]
	v_mfma_f32_16x16x32_bf16 v[100:103], v[182:185], v[206:209], v[100:103]
	v_mfma_f32_16x16x32_bf16 v[96:99], v[190:193], v[206:209], v[96:99]
	v_mfma_f32_16x16x32_bf16 v[84:87], v[182:185], v[214:217], v[84:87]
	v_mfma_f32_16x16x32_bf16 v[80:83], v[190:193], v[214:217], v[80:83]
	v_mfma_f32_16x16x32_bf16 v[68:71], v[182:185], v[222:225], v[68:71]
	v_mfma_f32_16x16x32_bf16 v[64:67], v[190:193], v[222:225], v[64:67]
	s_barrier
; #define PG8_STAGE(bufoff, gbase, voff) do { _Pragma("unroll") for (int _i = 0; _i < 2; ++_i) \
;         __builtin_amdgcn_global_load_lds((const unsigned*)((const char*)(gbase) + (voff)[_i]), (PG8_LAS unsigned*)(lds + (bufoff) + ldsw + _i * 8192), 16, 0, 0); } while (0)
; #define PG8_LDA(dst, b, h) do { _Pragma("unroll") for (int m = 0; m < 4; ++m) _Pragma("unroll") for (int k = 0; k < 2; ++k) dst[m][k] = *(const PG8_LAS bf16x8*)(lds + PG8_SA(b, h) + aoff + m * 2048 + k * 1024); } while (0)
; #define PG8_MMA(ai, bj, At, Bt) do { __builtin_amdgcn_s_setprio(1); _Pragma("unroll") for (int m = 0; m < 4; ++m) _Pragma("unroll") for (int n = 0; n < 2; ++n) _Pragma("unroll") for (int k = 0; k < 2; ++k) \
;         acc[ai][bj][m][n] = __builtin_amdgcn_mfma_f32_16x16x32_bf16(Bt[n][k], At[m][k], acc[ai][bj][m][n], 0, 0, 0); __builtin_amdgcn_s_setprio(0); } while (0)
; #define PG8_WAIT_V(n) asm volatile("s_waitcnt vmcnt(" #n ")" ::: "memory")
; #define PG8_WAIT_L(n) asm volatile("s_waitcnt lgkmcnt(" #n ")" ::: "memory")
; #define PG8_BAR __builtin_amdgcn_s_barrier()
; #define PG8_SCHED __builtin_amdgcn_sched_barrier(0)
; template <class Epi, class Sched, bool ALIGN_EPI = false, bool SP2 = false>
; __device__ __forceinline__ void gemm_phase(PG8_LAS unsigned char* lds, const Gemm g, const Sched& S, const Epi& E, int tid_in) {
;     ...
;         for (int t = 0; t < nt; t += 2) {
;             const bool last = (t == nt - 2);
;             const char* a1 = cA + (size_t)(t + 1) * kstep;
;             const char* a2 = last ? nA : cA + (size_t)(t + 2) * kstep; const char* b2 = last ? nB : cB + (size_t)(t + 2) * kstep;
;             const char* a3 = a2 + kstep; const char* b3 = b2 + kstep;
;     ...
;             PG8_LDA(At, 1, 1); PG8_STAGE(PG8_SB(1, 0), b3, voffB); PG8_STAGE(PG8_SB(1, 1), b3 + hstep, voffB); PG8_STAGE(PG8_SA(1, 0), a3, voffA);
;             PG8_WAIT_V(8); PG8_WAIT_L(0); PG8_BAR; PG8_MMA(1, 0, At, B0); PG8_MMA(1, 1, At, B1); PG8_BAR; PG8_SCHED;
	s_add_i32 s4, s37, s42
	v_lshl_add_u64 v[144:145], v[144:145], 0, s[64:65]
	s_mov_b32 m0, s4
	ds_read_b128 v[194:197], v161 offset:49152
	ds_read_b128 v[198:201], v161 offset:50176
	ds_read_b128 v[202:205], v161 offset:51200
	ds_read_b128 v[206:209], v161 offset:52224
	ds_read_b128 v[210:213], v161 offset:53248
	ds_read_b128 v[214:217], v161 offset:54272
	ds_read_b128 v[218:221], v161 offset:55296
	ds_read_b128 v[222:225], v161 offset:56320
	global_load_lds_dwordx4 v[144:145], off
	v_lshl_add_u64 v[144:145], v[226:227], 0, s[64:65]
	s_add_i32 m0, s4, 0x2000
	s_add_i32 s4, s88, s42
	global_load_lds_dwordx4 v[144:145], off
	v_lshl_add_u64 v[144:145], v[228:229], 0, s[64:65]
	s_mov_b32 m0, s4
	s_nop 0
	global_load_lds_dwordx4 v[144:145], off
	v_lshl_add_u64 v[144:145], v[238:239], 0, s[64:65]
	s_add_i32 m0, s4, 0x2000
	s_nop 0
	global_load_lds_dwordx4 v[144:145], off
	v_lshl_add_u64 v[144:145], v[240:241], 0, s[64:65]
	s_mov_b32 m0, s34
	s_nop 0
	global_load_lds_dwordx4 v[144:145], off
	v_lshl_add_u64 v[144:145], v[242:243], 0, s[64:65]
	s_mov_b32 m0, s35
	s_nop 0
	global_load_lds_dwordx4 v[144:145], off
	s_waitcnt vmcnt(8)
	s_waitcnt lgkmcnt(0)
	s_barrier
	s_waitcnt lgkmcnt(0)
	v_mfma_f32_16x16x32_bf16 v[60:63], v[140:143], v[194:197], v[60:63]
	v_mfma_f32_16x16x32_bf16 v[56:59], v[170:173], v[194:197], v[56:59]
	v_mfma_f32_16x16x32_bf16 v[44:47], v[140:143], v[202:205], v[44:47]
	v_mfma_f32_16x16x32_bf16 v[40:43], v[170:173], v[202:205], v[40:43]
	v_mfma_f32_16x16x32_bf16 v[28:31], v[140:143], v[210:213], v[28:31]
	v_mfma_f32_16x16x32_bf16 v[24:27], v[170:173], v[210:213], v[24:27]
	v_mfma_f32_16x16x32_bf16 v[12:15], v[140:143], v[218:221], v[12:15]
	v_mfma_f32_16x16x32_bf16 v[8:11], v[170:173], v[218:221], v[8:11]
	v_mfma_f32_16x16x32_bf16 v[60:63], v[166:169], v[198:201], v[60:63]
	v_mfma_f32_16x16x32_bf16 v[56:59], v[174:177], v[198:201], v[56:59]
	v_mfma_f32_16x16x32_bf16 v[44:47], v[166:169], v[206:209], v[44:47]
	v_mfma_f32_16x16x32_bf16 v[40:43], v[174:177], v[206:209], v[40:43]
	v_mfma_f32_16x16x32_bf16 v[28:31], v[166:169], v[214:217], v[28:31]
	v_mfma_f32_16x16x32_bf16 v[24:27], v[174:177], v[214:217], v[24:27]
	v_mfma_f32_16x16x32_bf16 v[12:15], v[166:169], v[222:225], v[12:15]
	v_mfma_f32_16x16x32_bf16 v[8:11], v[174:177], v[222:225], v[8:11]
	v_mfma_f32_16x16x32_bf16 v[52:55], v[178:181], v[194:197], v[52:55]
	v_mfma_f32_16x16x32_bf16 v[48:51], v[186:189], v[194:197], v[48:51]
	v_mfma_f32_16x16x32_bf16 v[36:39], v[178:181], v[202:205], v[36:39]
	v_mfma_f32_16x16x32_bf16 v[32:35], v[186:189], v[202:205], v[32:35]
	v_mfma_f32_16x16x32_bf16 v[20:23], v[178:181], v[210:213], v[20:23]
	v_mfma_f32_16x16x32_bf16 v[16:19], v[186:189], v[210:213], v[16:19]
	v_mfma_f32_16x16x32_bf16 v[4:7], v[178:181], v[218:221], v[4:7]
	v_mfma_f32_16x16x32_bf16 v[0:3], v[186:189], v[218:221], v[0:3]
	v_mfma_f32_16x16x32_bf16 v[52:55], v[182:185], v[198:201], v[52:55]
	v_mfma_f32_16x16x32_bf16 v[48:51], v[190:193], v[198:201], v[48:51]
	v_mfma_f32_16x16x32_bf16 v[36:39], v[182:185], v[206:209], v[36:39]
	v_mfma_f32_16x16x32_bf16 v[32:35], v[190:193], v[206:209], v[32:35]
	v_mfma_f32_16x16x32_bf16 v[20:23], v[182:185], v[214:217], v[20:23]
	v_mfma_f32_16x16x32_bf16 v[16:19], v[190:193], v[214:217], v[16:19]
	v_mfma_f32_16x16x32_bf16 v[4:7], v[182:185], v[222:225], v[4:7]
	v_mfma_f32_16x16x32_bf16 v[0:3], v[190:193], v[222:225], v[0:3]
	s_barrier
	s_add_u32 s0, s0, 0x100
	s_addc_u32 s1, s1, 0
	s_add_u32 s22, s22, 0x100
	s_addc_u32 s23, s23, 0
	s_cmp_ge_i32 s36, s55
	s_mov_b32 s4, s36
	s_cbranch_scc0 .LBB0_151
	s_mov_b32 s88, 0x3a000000

; #define PG8_STAGE(bufoff, gbase, voff) do { _Pragma("unroll") for (int _i = 0; _i < 2; ++_i) \
;         __builtin_amdgcn_global_load_lds((const unsigned*)((const char*)(gbase) + (voff)[_i]), (PG8_LAS unsigned*)(lds + (bufoff) + ldsw + _i * 8192), 16, 0, 0); } while (0)
; #define PG8_LDA(dst, b, h) do { _Pragma("unroll") for (int m = 0; m < 4; ++m) _Pragma("unroll") for (int k = 0; k < 2; ++k) dst[m][k] = *(const PG8_LAS bf16x8*)(lds + PG8_SA(b, h) + aoff + m * 2048 + k * 1024); } while (0)
; #define PG8_LDB(dst, b, h) do { _Pragma("unroll") for (int n = 0; n < 2; ++n) _Pragma("unroll") for (int k = 0; k < 2; ++k) dst[n][k] = *(const PG8_LAS bf16x8*)(lds + PG8_SB(b, h) + boff + n * 2048 + k * 1024); } while (0)
; #define PG8_MMA(ai, bj, At, Bt) do { __builtin_amdgcn_s_setprio(1); _Pragma("unroll") for (int m = 0; m < 4; ++m) _Pragma("unroll") for (int n = 0; n < 2; ++n) _Pragma("unroll") for (int k = 0; k < 2; ++k) \
;         acc[ai][bj][m][n] = __builtin_amdgcn_mfma_f32_16x16x32_bf16(Bt[n][k], At[m][k], acc[ai][bj][m][n], 0, 0, 0); __builtin_amdgcn_s_setprio(0); } while (0)
; #define PG8_WAIT_V(n) asm volatile("s_waitcnt vmcnt(" #n ")" ::: "memory")
; #define PG8_WAIT_L(n) asm volatile("s_waitcnt lgkmcnt(" #n ")" ::: "memory")
; #define PG8_BAR __builtin_amdgcn_s_barrier()
; #define PG8_SCHED __builtin_amdgcn_sched_barrier(0)
; template <class Epi, class Sched, bool ALIGN_EPI = false, bool SP2 = false>
; __device__ __forceinline__ void gemm_phase(PG8_LAS unsigned char* lds, const Gemm g, const Sched& S, const Epi& E, int tid_in) {
;     ...
;             PG8_LDB(B0, 0, 0); PG8_LDB(B1, 0, 1); PG8_SCHED; PG8_LDA(At, 0, 0); PG8_STAGE(PG8_SA(1, 1), a1 + hstep, voffA);
;             PG8_WAIT_V(8); PG8_WAIT_L(0); PG8_BAR; PG8_MMA(0, 0, At, B0); PG8_MMA(0, 1, At, B1); PG8_BAR; PG8_SCHED;
;             PG8_LDA(At, 0, 1); PG8_STAGE(PG8_SB(0, 0), b2, voffB); PG8_STAGE(PG8_SB(0, 1), b2 + hstep, voffB); PG8_STAGE(PG8_SA(0, 0), a2, voffA);
;             PG8_WAIT_V(8); PG8_WAIT_L(0); PG8_BAR; PG8_MMA(1, 0, At, B0); PG8_MMA(1, 1, At, B1); PG8_BAR; PG8_SCHED;
.LBB0_820:
	s_add_i32 s36, s22, 2
	s_add_u32 s2, s0, 0x80
	s_addc_u32 s3, s1, 0
	s_add_i32 s37, 0, 0x10000
	s_cmp_eq_u32 s90, s22
	s_cselect_b32 s23, s9, s3
	s_cselect_b32 s22, s8, s2
	s_cselect_b32 s3, s55, vcc_lo
	s_cselect_b32 s2, s54, s63
	s_add_i32 vcc_hi, 0, 0x14000
	v_add_u32_e32 v146, s37, v237
	v_add_u32_e32 v154, vcc_hi, v237
	ds_read_b128 v[134:137], v146
	ds_read_b128 v[138:141], v146 offset:1024
	ds_read_b128 v[142:145], v146 offset:2048
	ds_read_b128 v[146:149], v146 offset:3072
	ds_read_b128 v[150:153], v154
	ds_read_b128 v[166:169], v154 offset:1024
	ds_read_b128 v[170:173], v154 offset:2048
	ds_read_b128 v[174:177], v154 offset:3072
	v_lshl_add_u64 v[154:155], s[0:1], 0, v[130:131]
	s_add_i32 m0, s47, 0xc000
	ds_read_b128 v[178:181], v241
	ds_read_b128 v[182:185], v241 offset:1024
	ds_read_b128 v[186:189], v241 offset:2048
	ds_read_b128 v[190:193], v241 offset:3072
	ds_read_b128 v[194:197], v241 offset:4096
	ds_read_b128 v[198:201], v241 offset:5120
	ds_read_b128 v[202:205], v241 offset:6144
	ds_read_b128 v[206:209], v241 offset:7168
	global_load_lds_dwordx4 v[154:155], off
	v_lshl_add_u64 v[154:155], s[0:1], 0, v[132:133]
	s_add_i32 m0, s47, 0xe000
	s_nop 0
	global_load_lds_dwordx4 v[154:155], off
	s_waitcnt vmcnt(8)
	s_waitcnt lgkmcnt(0)
	s_barrier
	s_waitcnt lgkmcnt(0)
	v_mfma_f32_16x16x32_bf16 v[124:127], v[134:137], v[178:181], v[124:127]
	v_mfma_f32_16x16x32_bf16 v[120:123], v[142:145], v[178:181], v[120:123]
	v_mfma_f32_16x16x32_bf16 v[108:111], v[134:137], v[186:189], v[108:111]
	v_mfma_f32_16x16x32_bf16 v[104:107], v[142:145], v[186:189], v[104:107]
	v_mfma_f32_16x16x32_bf16 v[92:95], v[134:137], v[194:197], v[92:95]
	v_mfma_f32_16x16x32_bf16 v[88:91], v[142:145], v[194:197], v[88:91]
	v_mfma_f32_16x16x32_bf16 v[76:79], v[134:137], v[202:205], v[76:79]
	v_mfma_f32_16x16x32_bf16 v[72:75], v[142:145], v[202:205], v[72:75]
	v_mfma_f32_16x16x32_bf16 v[124:127], v[138:141], v[182:185], v[124:127]
	v_mfma_f32_16x16x32_bf16 v[120:123], v[146:149], v[182:185], v[120:123]
	v_mfma_f32_16x16x32_bf16 v[108:111], v[138:141], v[190:193], v[108:111]
	v_mfma_f32_16x16x32_bf16 v[104:107], v[146:149], v[190:193], v[104:107]
	v_mfma_f32_16x16x32_bf16 v[92:95], v[138:141], v[198:201], v[92:95]
	v_mfma_f32_16x16x32_bf16 v[88:91], v[146:149], v[198:201], v[88:91]
	v_mfma_f32_16x16x32_bf16 v[76:79], v[138:141], v[206:209], v[76:79]
	v_mfma_f32_16x16x32_bf16 v[72:75], v[146:149], v[206:209], v[72:75]
	v_mfma_f32_16x16x32_bf16 v[116:119], v[150:153], v[178:181], v[116:119]
	v_mfma_f32_16x16x32_bf16 v[112:115], v[170:173], v[178:181], v[112:115]
	v_mfma_f32_16x16x32_bf16 v[100:103], v[150:153], v[186:189], v[100:103]
	v_mfma_f32_16x16x32_bf16 v[96:99], v[170:173], v[186:189], v[96:99]
	v_mfma_f32_16x16x32_bf16 v[84:87], v[150:153], v[194:197], v[84:87]
	v_mfma_f32_16x16x32_bf16 v[80:83], v[170:173], v[194:197], v[80:83]
	v_mfma_f32_16x16x32_bf16 v[68:71], v[150:153], v[202:205], v[68:71]
	v_mfma_f32_16x16x32_bf16 v[64:67], v[170:173], v[202:205], v[64:67]
	v_mfma_f32_16x16x32_bf16 v[116:119], v[166:169], v[182:185], v[116:119]
	v_mfma_f32_16x16x32_bf16 v[112:115], v[174:177], v[182:185], v[112:115]
	v_mfma_f32_16x16x32_bf16 v[100:103], v[166:169], v[190:193], v[100:103]
	v_mfma_f32_16x16x32_bf16 v[96:99], v[174:177], v[190:193], v[96:99]
	v_mfma_f32_16x16x32_bf16 v[84:87], v[166:169], v[198:201], v[84:87]
	v_mfma_f32_16x16x32_bf16 v[80:83], v[174:177], v[198:201], v[80:83]
	v_mfma_f32_16x16x32_bf16 v[68:71], v[166:169], v[206:209], v[68:71]
	v_mfma_f32_16x16x32_bf16 v[64:67], v[174:177], v[206:209], v[64:67]
	s_barrier
	s_add_i32 s37, s37, s46
	v_lshl_add_u64 v[154:155], s[2:3], 0, v[156:157]
	s_mov_b32 m0, s37
	ds_read_b128 v[178:181], v241 offset:16384
	ds_read_b128 v[182:185], v241 offset:17408
	ds_read_b128 v[186:189], v241 offset:18432
	ds_read_b128 v[190:193], v241 offset:19456
	ds_read_b128 v[194:197], v241 offset:20480
	ds_read_b128 v[198:201], v241 offset:21504
	ds_read_b128 v[202:205], v241 offset:22528
	ds_read_b128 v[206:209], v241 offset:23552
	global_load_lds_dwordx4 v[154:155], off
	s_add_i32 m0, s37, 0x2000
	v_lshl_add_u64 v[162:163], s[2:3], 0, v[128:129]
	s_add_u32 s2, s2, s12
	s_addc_u32 s3, s3, s13
	s_add_i32 s37, vcc_hi, s46
	global_load_lds_dwordx4 v[162:163], off
	v_lshl_add_u64 v[210:211], s[2:3], 0, v[156:157]
	s_mov_b32 m0, s37
	v_lshl_add_u64 v[212:213], s[2:3], 0, v[128:129]
	global_load_lds_dwordx4 v[210:211], off
	s_add_i32 m0, s37, 0x2000
	v_lshl_add_u64 v[214:215], s[22:23], 0, v[156:157]
	global_load_lds_dwordx4 v[212:213], off
	s_mov_b32 m0, s47
	v_lshl_add_u64 v[216:217], s[22:23], 0, v[128:129]
	global_load_lds_dwordx4 v[214:215], off
	s_mov_b32 m0, s52
	s_nop 0
	global_load_lds_dwordx4 v[216:217], off
	s_waitcnt vmcnt(8)
	s_waitcnt lgkmcnt(0)
	s_barrier
; #define PG8_STAGE(bufoff, gbase, voff) do { _Pragma("unroll") for (int _i = 0; _i < 2; ++_i) \
;         __builtin_amdgcn_global_load_lds((const unsigned*)((const char*)(gbase) + (voff)[_i]), (PG8_LAS unsigned*)(lds + (bufoff) + ldsw + _i * 8192), 16, 0, 0); } while (0)
; #define PG8_LDA(dst, b, h) do { _Pragma("unroll") for (int m = 0; m < 4; ++m) _Pragma("unroll") for (int k = 0; k < 2; ++k) dst[m][k] = *(const PG8_LAS bf16x8*)(lds + PG8_SA(b, h) + aoff + m * 2048 + k * 1024); } while (0)
; #define PG8_LDB(dst, b, h) do { _Pragma("unroll") for (int n = 0; n < 2; ++n) _Pragma("unroll") for (int k = 0; k < 2; ++k) dst[n][k] = *(const PG8_LAS bf16x8*)(lds + PG8_SB(b, h) + boff + n * 2048 + k * 1024); } while (0)
; #define PG8_MMA(ai, bj, At, Bt) do { __builtin_amdgcn_s_setprio(1); _Pragma("unroll") for (int m = 0; m < 4; ++m) _Pragma("unroll") for (int n = 0; n < 2; ++n) _Pragma("unroll") for (int k = 0; k < 2; ++k) \
;         acc[ai][bj][m][n] = __builtin_amdgcn_mfma_f32_16x16x32_bf16(Bt[n][k], At[m][k], acc[ai][bj][m][n], 0, 0, 0); __builtin_amdgcn_s_setprio(0); } while (0)
; #define PG8_WAIT_V(n) asm volatile("s_waitcnt vmcnt(" #n ")" ::: "memory")
; #define PG8_WAIT_L(n) asm volatile("s_waitcnt lgkmcnt(" #n ")" ::: "memory")
; #define PG8_BAR __builtin_amdgcn_s_barrier()
; #define PG8_SCHED __builtin_amdgcn_sched_barrier(0)
; template <class Epi, class Sched, bool ALIGN_EPI = false, bool SP2 = false>
; __device__ __forceinline__ void gemm_phase(PG8_LAS unsigned char* lds, const Gemm g, const Sched& S, const Epi& E, int tid_in) {
;     ...
;             PG8_WAIT_V(8); PG8_WAIT_L(0); PG8_BAR; PG8_MMA(1, 0, At, B0); PG8_MMA(1, 1, At, B1); PG8_BAR; PG8_SCHED;
;             PG8_LDB(B0, 1, 0); PG8_LDB(B1, 1, 1); PG8_SCHED; PG8_LDA(At, 1, 0); PG8_STAGE(PG8_SA(0, 1), a2 + hstep, voffA);
;             PG8_WAIT_V(8); PG8_WAIT_L(0); PG8_BAR; PG8_MMA(0, 0, At, B0); PG8_MMA(0, 1, At, B1); PG8_BAR; PG8_SCHED;
	s_waitcnt lgkmcnt(0)
	v_mfma_f32_16x16x32_bf16 v[60:63], v[134:137], v[178:181], v[60:63]
	v_mfma_f32_16x16x32_bf16 v[56:59], v[142:145], v[178:181], v[56:59]
	v_mfma_f32_16x16x32_bf16 v[44:47], v[134:137], v[186:189], v[44:47]
	v_mfma_f32_16x16x32_bf16 v[40:43], v[142:145], v[186:189], v[40:43]
	v_mfma_f32_16x16x32_bf16 v[28:31], v[134:137], v[194:197], v[28:31]
	v_mfma_f32_16x16x32_bf16 v[24:27], v[142:145], v[194:197], v[24:27]
	v_mfma_f32_16x16x32_bf16 v[12:15], v[134:137], v[202:205], v[12:15]
	v_mfma_f32_16x16x32_bf16 v[8:11], v[142:145], v[202:205], v[8:11]
	v_mfma_f32_16x16x32_bf16 v[60:63], v[138:141], v[182:185], v[60:63]
	v_mfma_f32_16x16x32_bf16 v[56:59], v[146:149], v[182:185], v[56:59]
	v_mfma_f32_16x16x32_bf16 v[44:47], v[138:141], v[190:193], v[44:47]
	v_mfma_f32_16x16x32_bf16 v[40:43], v[146:149], v[190:193], v[40:43]
	v_mfma_f32_16x16x32_bf16 v[28:31], v[138:141], v[198:201], v[28:31]
	v_mfma_f32_16x16x32_bf16 v[24:27], v[146:149], v[198:201], v[24:27]
	v_mfma_f32_16x16x32_bf16 v[12:15], v[138:141], v[206:209], v[12:15]
	v_mfma_f32_16x16x32_bf16 v[8:11], v[146:149], v[206:209], v[8:11]
	v_mfma_f32_16x16x32_bf16 v[52:55], v[150:153], v[178:181], v[52:55]
	v_mfma_f32_16x16x32_bf16 v[48:51], v[170:173], v[178:181], v[48:51]
	v_mfma_f32_16x16x32_bf16 v[36:39], v[150:153], v[186:189], v[36:39]
	v_mfma_f32_16x16x32_bf16 v[32:35], v[170:173], v[186:189], v[32:35]
	v_mfma_f32_16x16x32_bf16 v[20:23], v[150:153], v[194:197], v[20:23]
	v_mfma_f32_16x16x32_bf16 v[16:19], v[170:173], v[194:197], v[16:19]
	v_mfma_f32_16x16x32_bf16 v[4:7], v[150:153], v[202:205], v[4:7]
	v_mfma_f32_16x16x32_bf16 v[0:3], v[170:173], v[202:205], v[0:3]
	v_mfma_f32_16x16x32_bf16 v[52:55], v[166:169], v[182:185], v[52:55]
	v_mfma_f32_16x16x32_bf16 v[48:51], v[174:177], v[182:185], v[48:51]
	v_mfma_f32_16x16x32_bf16 v[36:39], v[166:169], v[190:193], v[36:39]
	v_mfma_f32_16x16x32_bf16 v[32:35], v[174:177], v[190:193], v[32:35]
	v_mfma_f32_16x16x32_bf16 v[20:23], v[166:169], v[198:201], v[20:23]
	v_mfma_f32_16x16x32_bf16 v[16:19], v[174:177], v[198:201], v[16:19]
	v_mfma_f32_16x16x32_bf16 v[4:7], v[166:169], v[206:209], v[4:7]
	v_mfma_f32_16x16x32_bf16 v[0:3], v[174:177], v[206:209], v[0:3]
	s_barrier
	s_add_i32 s37, 0, 0x18000
	s_add_i32 vcc_hi, 0, 0x1c000
	v_add_u32_e32 v146, s37, v237
	v_add_u32_e32 v174, vcc_hi, v237
	ds_read_b128 v[134:137], v146
	ds_read_b128 v[138:141], v146 offset:1024
	ds_read_b128 v[142:145], v146 offset:2048
	ds_read_b128 v[146:149], v146 offset:3072
	ds_read_b128 v[150:153], v174
	ds_read_b128 v[166:169], v174 offset:1024
	ds_read_b128 v[170:173], v174 offset:2048
	ds_read_b128 v[174:177], v174 offset:3072
	s_add_u32 s2, s22, s12
	s_addc_u32 s3, s23, s13
	s_mov_b32 m0, s53
	v_lshl_add_u64 v[218:219], s[2:3], 0, v[156:157]
	ds_read_b128 v[178:181], v241 offset:32768
	ds_read_b128 v[182:185], v241 offset:33792
	ds_read_b128 v[186:189], v241 offset:34816
	ds_read_b128 v[190:193], v241 offset:35840
	ds_read_b128 v[194:197], v241 offset:36864
	ds_read_b128 v[198:201], v241 offset:37888
	ds_read_b128 v[202:205], v241 offset:38912
	ds_read_b128 v[206:209], v241 offset:39936
	global_load_lds_dwordx4 v[218:219], off
	v_lshl_add_u64 v[218:219], s[2:3], 0, v[128:129]
	s_mov_b32 m0, s56
	s_nop 0
	global_load_lds_dwordx4 v[218:219], off
	s_waitcnt vmcnt(8)
	s_waitcnt lgkmcnt(0)
	s_barrier
	s_waitcnt lgkmcnt(0)
	v_mfma_f32_16x16x32_bf16 v[124:127], v[134:137], v[178:181], v[124:127]
	v_mfma_f32_16x16x32_bf16 v[120:123], v[142:145], v[178:181], v[120:123]
	v_mfma_f32_16x16x32_bf16 v[108:111], v[134:137], v[186:189], v[108:111]
	v_mfma_f32_16x16x32_bf16 v[104:107], v[142:145], v[186:189], v[104:107]
	v_mfma_f32_16x16x32_bf16 v[92:95], v[134:137], v[194:197], v[92:95]
	v_mfma_f32_16x16x32_bf16 v[88:91], v[142:145], v[194:197], v[88:91]
	v_mfma_f32_16x16x32_bf16 v[76:79], v[134:137], v[202:205], v[76:79]
	v_mfma_f32_16x16x32_bf16 v[72:75], v[142:145], v[202:205], v[72:75]
	v_mfma_f32_16x16x32_bf16 v[124:127], v[138:141], v[182:185], v[124:127]
	v_mfma_f32_16x16x32_bf16 v[120:123], v[146:149], v[182:185], v[120:123]
	v_mfma_f32_16x16x32_bf16 v[108:111], v[138:141], v[190:193], v[108:111]
	v_mfma_f32_16x16x32_bf16 v[104:107], v[146:149], v[190:193], v[104:107]
	v_mfma_f32_16x16x32_bf16 v[92:95], v[138:141], v[198:201], v[92:95]
	v_mfma_f32_16x16x32_bf16 v[88:91], v[146:149], v[198:201], v[88:91]
	v_mfma_f32_16x16x32_bf16 v[76:79], v[138:141], v[206:209], v[76:79]
	v_mfma_f32_16x16x32_bf16 v[72:75], v[146:149], v[206:209], v[72:75]
	v_mfma_f32_16x16x32_bf16 v[116:119], v[150:153], v[178:181], v[116:119]
	v_mfma_f32_16x16x32_bf16 v[112:115], v[170:173], v[178:181], v[112:115]
	v_mfma_f32_16x16x32_bf16 v[100:103], v[150:153], v[186:189], v[100:103]
	v_mfma_f32_16x16x32_bf16 v[96:99], v[170:173], v[186:189], v[96:99]
	v_mfma_f32_16x16x32_bf16 v[84:87], v[150:153], v[194:197], v[84:87]
	v_mfma_f32_16x16x32_bf16 v[80:83], v[170:173], v[194:197], v[80:83]
	v_mfma_f32_16x16x32_bf16 v[68:71], v[150:153], v[202:205], v[68:71]
	v_mfma_f32_16x16x32_bf16 v[64:67], v[170:173], v[202:205], v[64:67]
	v_mfma_f32_16x16x32_bf16 v[116:119], v[166:169], v[182:185], v[116:119]
	v_mfma_f32_16x16x32_bf16 v[112:115], v[174:177], v[182:185], v[112:115]
	v_mfma_f32_16x16x32_bf16 v[100:103], v[166:169], v[190:193], v[100:103]
	v_mfma_f32_16x16x32_bf16 v[96:99], v[174:177], v[190:193], v[96:99]
	v_mfma_f32_16x16x32_bf16 v[84:87], v[166:169], v[198:201], v[84:87]
	v_mfma_f32_16x16x32_bf16 v[80:83], v[174:177], v[198:201], v[80:83]
	v_mfma_f32_16x16x32_bf16 v[68:71], v[166:169], v[206:209], v[68:71]
	v_mfma_f32_16x16x32_bf16 v[64:67], v[174:177], v[206:209], v[64:67]
	s_barrier
; #define PG8_STAGE(bufoff, gbase, voff) do { _Pragma("unroll") for (int _i = 0; _i < 2; ++_i) \
;         __builtin_amdgcn_global_load_lds((const unsigned*)((const char*)(gbase) + (voff)[_i]), (PG8_LAS unsigned*)(lds + (bufoff) + ldsw + _i * 8192), 16, 0, 0); } while (0)
; #define PG8_LDA(dst, b, h) do { _Pragma("unroll") for (int m = 0; m < 4; ++m) _Pragma("unroll") for (int k = 0; k < 2; ++k) dst[m][k] = *(const PG8_LAS bf16x8*)(lds + PG8_SA(b, h) + aoff + m * 2048 + k * 1024); } while (0)
; #define PG8_MMA(ai, bj, At, Bt) do { __builtin_amdgcn_s_setprio(1); _Pragma("unroll") for (int m = 0; m < 4; ++m) _Pragma("unroll") for (int n = 0; n < 2; ++n) _Pragma("unroll") for (int k = 0; k < 2; ++k) \
;         acc[ai][bj][m][n] = __builtin_amdgcn_mfma_f32_16x16x32_bf16(Bt[n][k], At[m][k], acc[ai][bj][m][n], 0, 0, 0); __builtin_amdgcn_s_setprio(0); } while (0)
; #define PG8_WAIT_V(n) asm volatile("s_waitcnt vmcnt(" #n ")" ::: "memory")
; #define PG8_WAIT_L(n) asm volatile("s_waitcnt lgkmcnt(" #n ")" ::: "memory")
; #define PG8_BAR __builtin_amdgcn_s_barrier()
; #define PG8_SCHED __builtin_amdgcn_sched_barrier(0)
; template <class Epi, class Sched, bool ALIGN_EPI = false, bool SP2 = false>
; __device__ __forceinline__ void gemm_phase(PG8_LAS unsigned char* lds, const Gemm g, const Sched& S, const Epi& E, int tid_in) {
;     ...
;         for (int t = 0; t < nt; t += 2) {
;             const bool last = (t == nt - 2);
;             const char* a1 = cA + (size_t)(t + 1) * kstep;
;             const char* a2 = last ? nA : cA + (size_t)(t + 2) * kstep; const char* b2 = last ? nB : cB + (size_t)(t + 2) * kstep;
;             const char* a3 = a2 + kstep; const char* b3 = b2 + kstep;
;     ...
;             PG8_LDA(At, 1, 1); PG8_STAGE(PG8_SB(1, 0), b3, voffB); PG8_STAGE(PG8_SB(1, 1), b3 + hstep, voffB); PG8_STAGE(PG8_SA(1, 0), a3, voffA);
;             PG8_WAIT_V(8); PG8_WAIT_L(0); PG8_BAR; PG8_MMA(1, 0, At, B0); PG8_MMA(1, 1, At, B1); PG8_BAR; PG8_SCHED;
	s_add_i32 s2, s37, s46
	v_lshl_add_u64 v[154:155], v[154:155], 0, s[64:65]
	s_mov_b32 m0, s2
	ds_read_b128 v[178:181], v241 offset:49152
	ds_read_b128 v[182:185], v241 offset:50176
	ds_read_b128 v[186:189], v241 offset:51200
	ds_read_b128 v[190:193], v241 offset:52224
	ds_read_b128 v[194:197], v241 offset:53248
	ds_read_b128 v[198:201], v241 offset:54272
	ds_read_b128 v[202:205], v241 offset:55296
	ds_read_b128 v[206:209], v241 offset:56320
	global_load_lds_dwordx4 v[154:155], off
	v_lshl_add_u64 v[154:155], v[162:163], 0, s[64:65]
	s_add_i32 m0, s2, 0x2000
	s_add_i32 s2, vcc_hi, s46
	global_load_lds_dwordx4 v[154:155], off
	v_lshl_add_u64 v[154:155], v[210:211], 0, s[64:65]
	s_mov_b32 m0, s2
	s_nop 0
	global_load_lds_dwordx4 v[154:155], off
	v_lshl_add_u64 v[154:155], v[212:213], 0, s[64:65]
	s_add_i32 m0, s2, 0x2000
	s_nop 0
	global_load_lds_dwordx4 v[154:155], off
	v_lshl_add_u64 v[154:155], v[214:215], 0, s[64:65]
	s_mov_b32 m0, s88
	s_nop 0
	global_load_lds_dwordx4 v[154:155], off
	v_lshl_add_u64 v[154:155], v[216:217], 0, s[64:65]
	s_mov_b32 m0, s89
	s_nop 0
	global_load_lds_dwordx4 v[154:155], off
	s_waitcnt vmcnt(8)
	s_waitcnt lgkmcnt(0)
	s_barrier
	s_waitcnt lgkmcnt(0)
	v_mfma_f32_16x16x32_bf16 v[60:63], v[134:137], v[178:181], v[60:63]
	v_mfma_f32_16x16x32_bf16 v[56:59], v[142:145], v[178:181], v[56:59]
	v_mfma_f32_16x16x32_bf16 v[44:47], v[134:137], v[186:189], v[44:47]
	v_mfma_f32_16x16x32_bf16 v[40:43], v[142:145], v[186:189], v[40:43]
	v_mfma_f32_16x16x32_bf16 v[28:31], v[134:137], v[194:197], v[28:31]
	v_mfma_f32_16x16x32_bf16 v[24:27], v[142:145], v[194:197], v[24:27]
	v_mfma_f32_16x16x32_bf16 v[12:15], v[134:137], v[202:205], v[12:15]
	v_mfma_f32_16x16x32_bf16 v[8:11], v[142:145], v[202:205], v[8:11]
	v_mfma_f32_16x16x32_bf16 v[60:63], v[138:141], v[182:185], v[60:63]
	v_mfma_f32_16x16x32_bf16 v[56:59], v[146:149], v[182:185], v[56:59]
	v_mfma_f32_16x16x32_bf16 v[44:47], v[138:141], v[190:193], v[44:47]
	v_mfma_f32_16x16x32_bf16 v[40:43], v[146:149], v[190:193], v[40:43]
	v_mfma_f32_16x16x32_bf16 v[28:31], v[138:141], v[198:201], v[28:31]
	v_mfma_f32_16x16x32_bf16 v[24:27], v[146:149], v[198:201], v[24:27]
	v_mfma_f32_16x16x32_bf16 v[12:15], v[138:141], v[206:209], v[12:15]
	v_mfma_f32_16x16x32_bf16 v[8:11], v[146:149], v[206:209], v[8:11]
	v_mfma_f32_16x16x32_bf16 v[52:55], v[150:153], v[178:181], v[52:55]
	v_mfma_f32_16x16x32_bf16 v[48:51], v[170:173], v[178:181], v[48:51]
	v_mfma_f32_16x16x32_bf16 v[36:39], v[150:153], v[186:189], v[36:39]
	v_mfma_f32_16x16x32_bf16 v[32:35], v[170:173], v[186:189], v[32:35]
	v_mfma_f32_16x16x32_bf16 v[20:23], v[150:153], v[194:197], v[20:23]
	v_mfma_f32_16x16x32_bf16 v[16:19], v[170:173], v[194:197], v[16:19]
	v_mfma_f32_16x16x32_bf16 v[4:7], v[150:153], v[202:205], v[4:7]
	v_mfma_f32_16x16x32_bf16 v[0:3], v[170:173], v[202:205], v[0:3]
	v_mfma_f32_16x16x32_bf16 v[52:55], v[166:169], v[182:185], v[52:55]
	v_mfma_f32_16x16x32_bf16 v[48:51], v[174:177], v[182:185], v[48:51]
	v_mfma_f32_16x16x32_bf16 v[36:39], v[166:169], v[190:193], v[36:39]
	v_mfma_f32_16x16x32_bf16 v[32:35], v[174:177], v[190:193], v[32:35]
	v_mfma_f32_16x16x32_bf16 v[20:23], v[166:169], v[198:201], v[20:23]
	v_mfma_f32_16x16x32_bf16 v[16:19], v[174:177], v[198:201], v[16:19]
	v_mfma_f32_16x16x32_bf16 v[4:7], v[166:169], v[206:209], v[4:7]
	v_mfma_f32_16x16x32_bf16 v[0:3], v[174:177], v[206:209], v[0:3]
	s_barrier
	s_add_u32 s0, s0, 0x100
	s_addc_u32 s1, s1, 0
	s_add_u32 s63, s63, 0x100
	s_addc_u32 vcc_lo, vcc_lo, 0
	s_cmp_ge_i32 s36, s67
	s_mov_b32 s22, s36
	s_cbranch_scc0 .LBB0_820

; #define PG8_STAGE(bufoff, gbase, voff) do { _Pragma("unroll") for (int _i = 0; _i < 2; ++_i) \
;         __builtin_amdgcn_global_load_lds((const unsigned*)((const char*)(gbase) + (voff)[_i]), (PG8_LAS unsigned*)(lds + (bufoff) + ldsw + _i * 8192), 16, 0, 0); } while (0)
; #define PG8_LDA(dst, b, h) do { _Pragma("unroll") for (int m = 0; m < 4; ++m) _Pragma("unroll") for (int k = 0; k < 2; ++k) dst[m][k] = *(const PG8_LAS bf16x8*)(lds + PG8_SA(b, h) + aoff + m * 2048 + k * 1024); } while (0)
; #define PG8_LDB(dst, b, h) do { _Pragma("unroll") for (int n = 0; n < 2; ++n) _Pragma("unroll") for (int k = 0; k < 2; ++k) dst[n][k] = *(const PG8_LAS bf16x8*)(lds + PG8_SB(b, h) + boff + n * 2048 + k * 1024); } while (0)
; #define PG8_MMA(ai, bj, At, Bt) do { __builtin_amdgcn_s_setprio(1); _Pragma("unroll") for (int m = 0; m < 4; ++m) _Pragma("unroll") for (int n = 0; n < 2; ++n) _Pragma("unroll") for (int k = 0; k < 2; ++k) \
;         acc[ai][bj][m][n] = __builtin_amdgcn_mfma_f32_16x16x32_bf16(Bt[n][k], At[m][k], acc[ai][bj][m][n], 0, 0, 0); __builtin_amdgcn_s_setprio(0); } while (0)
; #define PG8_WAIT_V(n) asm volatile("s_waitcnt vmcnt(" #n ")" ::: "memory")
; #define PG8_WAIT_L(n) asm volatile("s_waitcnt lgkmcnt(" #n ")" ::: "memory")
; #define PG8_BAR __builtin_amdgcn_s_barrier()
; #define PG8_SCHED __builtin_amdgcn_sched_barrier(0)
; template <class Epi, class Sched, bool ALIGN_EPI = false, bool SP2 = false>
; __device__ __forceinline__ void gemm_phase(PG8_LAS unsigned char* lds, const Gemm g, const Sched& S, const Epi& E, int tid_in) {
;     ...
;             PG8_LDB(B0, 0, 0); PG8_LDB(B1, 0, 1); PG8_SCHED; PG8_LDA(At, 0, 0); PG8_STAGE(PG8_SA(1, 1), a1 + hstep, voffA);
;             PG8_WAIT_V(8); PG8_WAIT_L(0); PG8_BAR; PG8_MMA(0, 0, At, B0); PG8_MMA(0, 1, At, B1); PG8_BAR; PG8_SCHED;
;             PG8_LDA(At, 0, 1); PG8_STAGE(PG8_SB(0, 0), b2, voffB); PG8_STAGE(PG8_SB(0, 1), b2 + hstep, voffB); PG8_STAGE(PG8_SA(0, 0), a2, voffA);
;             PG8_WAIT_V(8); PG8_WAIT_L(0); PG8_BAR; PG8_MMA(1, 0, At, B0); PG8_MMA(1, 1, At, B1); PG8_BAR; PG8_SCHED;
.LBB0_928:
	s_add_i32 s36, s6, 2
	s_add_u32 s2, s0, 0x80
	s_addc_u32 s3, s1, 0
	s_add_i32 s37, 0, 0x10000
	s_cmp_eq_u32 s60, s6
	s_cselect_b32 s7, s63, s3
	s_cselect_b32 s6, s62, s2
	v_add_u32_e32 v144, s37, v151
	s_cselect_b32 s3, s67, s23
	s_cselect_b32 s2, s66, s22
	s_add_i32 s91, 0, 0x14000
	ds_read_b128 v[140:143], v144
	ds_read_b128 v[168:171], v144 offset:1024
	ds_read_b128 v[172:175], v144 offset:2048
	ds_read_b128 v[176:179], v144 offset:3072
	v_add_u32_e32 v144, s91, v151
	ds_read_b128 v[180:183], v144
	ds_read_b128 v[184:187], v144 offset:1024
	ds_read_b128 v[188:191], v144 offset:2048
	ds_read_b128 v[192:195], v144 offset:3072
	v_lshl_add_u64 v[146:147], s[0:1], 0, v[136:137]
	s_add_i32 m0, s43, 0xc000
	ds_read_b128 v[196:199], v167
	ds_read_b128 v[200:203], v167 offset:1024
	ds_read_b128 v[204:207], v167 offset:2048
	ds_read_b128 v[208:211], v167 offset:3072
	ds_read_b128 v[212:215], v167 offset:4096
	ds_read_b128 v[216:219], v167 offset:5120
	ds_read_b128 v[220:223], v167 offset:6144
	ds_read_b128 v[224:227], v167 offset:7168
	global_load_lds_dwordx4 v[146:147], off
	v_lshl_add_u64 v[146:147], s[0:1], 0, v[138:139]
	s_add_i32 m0, s43, 0xe000
	s_nop 0
	global_load_lds_dwordx4 v[146:147], off
	s_waitcnt vmcnt(8)
	s_waitcnt lgkmcnt(0)
	s_barrier
	s_waitcnt lgkmcnt(0)
	v_mfma_f32_16x16x32_bf16 v[124:127], v[140:143], v[196:199], v[124:127]
	v_mfma_f32_16x16x32_bf16 v[120:123], v[172:175], v[196:199], v[120:123]
	v_mfma_f32_16x16x32_bf16 v[108:111], v[140:143], v[204:207], v[108:111]
	v_mfma_f32_16x16x32_bf16 v[104:107], v[172:175], v[204:207], v[104:107]
	v_mfma_f32_16x16x32_bf16 v[92:95], v[140:143], v[212:215], v[92:95]
	v_mfma_f32_16x16x32_bf16 v[88:91], v[172:175], v[212:215], v[88:91]
	v_mfma_f32_16x16x32_bf16 v[76:79], v[140:143], v[220:223], v[76:79]
	v_mfma_f32_16x16x32_bf16 v[72:75], v[172:175], v[220:223], v[72:75]
	v_mfma_f32_16x16x32_bf16 v[124:127], v[168:171], v[200:203], v[124:127]
	v_mfma_f32_16x16x32_bf16 v[120:123], v[176:179], v[200:203], v[120:123]
	v_mfma_f32_16x16x32_bf16 v[108:111], v[168:171], v[208:211], v[108:111]
	v_mfma_f32_16x16x32_bf16 v[104:107], v[176:179], v[208:211], v[104:107]
	v_mfma_f32_16x16x32_bf16 v[92:95], v[168:171], v[216:219], v[92:95]
	v_mfma_f32_16x16x32_bf16 v[88:91], v[176:179], v[216:219], v[88:91]
	v_mfma_f32_16x16x32_bf16 v[76:79], v[168:171], v[224:227], v[76:79]
	v_mfma_f32_16x16x32_bf16 v[72:75], v[176:179], v[224:227], v[72:75]
	v_mfma_f32_16x16x32_bf16 v[116:119], v[180:183], v[196:199], v[116:119]
	v_mfma_f32_16x16x32_bf16 v[112:115], v[188:191], v[196:199], v[112:115]
	v_mfma_f32_16x16x32_bf16 v[100:103], v[180:183], v[204:207], v[100:103]
	v_mfma_f32_16x16x32_bf16 v[96:99], v[188:191], v[204:207], v[96:99]
	v_mfma_f32_16x16x32_bf16 v[84:87], v[180:183], v[212:215], v[84:87]
	v_mfma_f32_16x16x32_bf16 v[80:83], v[188:191], v[212:215], v[80:83]
	v_mfma_f32_16x16x32_bf16 v[68:71], v[180:183], v[220:223], v[68:71]
	v_mfma_f32_16x16x32_bf16 v[64:67], v[188:191], v[220:223], v[64:67]
	v_mfma_f32_16x16x32_bf16 v[116:119], v[184:187], v[200:203], v[116:119]
	v_mfma_f32_16x16x32_bf16 v[112:115], v[192:195], v[200:203], v[112:115]
	v_mfma_f32_16x16x32_bf16 v[100:103], v[184:187], v[208:211], v[100:103]
	v_mfma_f32_16x16x32_bf16 v[96:99], v[192:195], v[208:211], v[96:99]
	v_mfma_f32_16x16x32_bf16 v[84:87], v[184:187], v[216:219], v[84:87]
	v_mfma_f32_16x16x32_bf16 v[80:83], v[192:195], v[216:219], v[80:83]
	v_mfma_f32_16x16x32_bf16 v[68:71], v[184:187], v[224:227], v[68:71]
	v_mfma_f32_16x16x32_bf16 v[64:67], v[192:195], v[224:227], v[64:67]
	s_barrier
	s_add_i32 s37, s37, s42
	v_lshl_add_u64 v[146:147], s[2:3], 0, v[156:157]
	s_mov_b32 m0, s37
	ds_read_b128 v[196:199], v167 offset:16384
	ds_read_b128 v[200:203], v167 offset:17408
	ds_read_b128 v[204:207], v167 offset:18432
	ds_read_b128 v[208:211], v167 offset:19456
	ds_read_b128 v[212:215], v167 offset:20480
	ds_read_b128 v[216:219], v167 offset:21504
	ds_read_b128 v[220:223], v167 offset:22528
	ds_read_b128 v[224:227], v167 offset:23552
	global_load_lds_dwordx4 v[146:147], off
	s_add_i32 m0, s37, 0x2000
	v_lshl_add_u64 v[162:163], s[2:3], 0, v[128:129]
	s_add_u32 s2, s2, s10
	s_addc_u32 s3, s3, s11
	s_add_i32 s37, s91, s42
	global_load_lds_dwordx4 v[162:163], off
	v_lshl_add_u64 v[228:229], s[2:3], 0, v[156:157]
	s_mov_b32 m0, s37
	v_lshl_add_u64 v[230:231], s[2:3], 0, v[128:129]
	global_load_lds_dwordx4 v[228:229], off
	s_add_i32 m0, s37, 0x2000
	v_lshl_add_u64 v[238:239], s[6:7], 0, v[132:133]
	global_load_lds_dwordx4 v[230:231], off
	s_mov_b32 m0, s43
	v_lshl_add_u64 v[240:241], s[6:7], 0, v[130:131]
	global_load_lds_dwordx4 v[238:239], off
	s_mov_b32 m0, s44
	s_nop 0
	global_load_lds_dwordx4 v[240:241], off
	s_waitcnt vmcnt(8)
	s_waitcnt lgkmcnt(0)
	s_barrier
; #define PG8_STAGE(bufoff, gbase, voff) do { _Pragma("unroll") for (int _i = 0; _i < 2; ++_i) \
;         __builtin_amdgcn_global_load_lds((const unsigned*)((const char*)(gbase) + (voff)[_i]), (PG8_LAS unsigned*)(lds + (bufoff) + ldsw + _i * 8192), 16, 0, 0); } while (0)
; #define PG8_LDA(dst, b, h) do { _Pragma("unroll") for (int m = 0; m < 4; ++m) _Pragma("unroll") for (int k = 0; k < 2; ++k) dst[m][k] = *(const PG8_LAS bf16x8*)(lds + PG8_SA(b, h) + aoff + m * 2048 + k * 1024); } while (0)
; #define PG8_LDB(dst, b, h) do { _Pragma("unroll") for (int n = 0; n < 2; ++n) _Pragma("unroll") for (int k = 0; k < 2; ++k) dst[n][k] = *(const PG8_LAS bf16x8*)(lds + PG8_SB(b, h) + boff + n * 2048 + k * 1024); } while (0)
; #define PG8_MMA(ai, bj, At, Bt) do { __builtin_amdgcn_s_setprio(1); _Pragma("unroll") for (int m = 0; m < 4; ++m) _Pragma("unroll") for (int n = 0; n < 2; ++n) _Pragma("unroll") for (int k = 0; k < 2; ++k) \
;         acc[ai][bj][m][n] = __builtin_amdgcn_mfma_f32_16x16x32_bf16(Bt[n][k], At[m][k], acc[ai][bj][m][n], 0, 0, 0); __builtin_amdgcn_s_setprio(0); } while (0)
; #define PG8_WAIT_V(n) asm volatile("s_waitcnt vmcnt(" #n ")" ::: "memory")
; #define PG8_WAIT_L(n) asm volatile("s_waitcnt lgkmcnt(" #n ")" ::: "memory")
; #define PG8_BAR __builtin_amdgcn_s_barrier()
; #define PG8_SCHED __builtin_amdgcn_sched_barrier(0)
; template <class Epi, class Sched, bool ALIGN_EPI = false, bool SP2 = false>
; __device__ __forceinline__ void gemm_phase(PG8_LAS unsigned char* lds, const Gemm g, const Sched& S, const Epi& E, int tid_in) {
;     ...
;             PG8_WAIT_V(8); PG8_WAIT_L(0); PG8_BAR; PG8_MMA(1, 0, At, B0); PG8_MMA(1, 1, At, B1); PG8_BAR; PG8_SCHED;
;             PG8_LDB(B0, 1, 0); PG8_LDB(B1, 1, 1); PG8_SCHED; PG8_LDA(At, 1, 0); PG8_STAGE(PG8_SA(0, 1), a2 + hstep, voffA);
;             PG8_WAIT_V(8); PG8_WAIT_L(0); PG8_BAR; PG8_MMA(0, 0, At, B0); PG8_MMA(0, 1, At, B1); PG8_BAR; PG8_SCHED;
	s_waitcnt lgkmcnt(0)
	v_mfma_f32_16x16x32_bf16 v[60:63], v[140:143], v[196:199], v[60:63]
	v_mfma_f32_16x16x32_bf16 v[56:59], v[172:175], v[196:199], v[56:59]
	v_mfma_f32_16x16x32_bf16 v[44:47], v[140:143], v[204:207], v[44:47]
	v_mfma_f32_16x16x32_bf16 v[40:43], v[172:175], v[204:207], v[40:43]
	v_mfma_f32_16x16x32_bf16 v[28:31], v[140:143], v[212:215], v[28:31]
	v_mfma_f32_16x16x32_bf16 v[24:27], v[172:175], v[212:215], v[24:27]
	v_mfma_f32_16x16x32_bf16 v[12:15], v[140:143], v[220:223], v[12:15]
	v_mfma_f32_16x16x32_bf16 v[8:11], v[172:175], v[220:223], v[8:11]
	v_mfma_f32_16x16x32_bf16 v[60:63], v[168:171], v[200:203], v[60:63]
	v_mfma_f32_16x16x32_bf16 v[56:59], v[176:179], v[200:203], v[56:59]
	v_mfma_f32_16x16x32_bf16 v[44:47], v[168:171], v[208:211], v[44:47]
	v_mfma_f32_16x16x32_bf16 v[40:43], v[176:179], v[208:211], v[40:43]
	v_mfma_f32_16x16x32_bf16 v[28:31], v[168:171], v[216:219], v[28:31]
	v_mfma_f32_16x16x32_bf16 v[24:27], v[176:179], v[216:219], v[24:27]
	v_mfma_f32_16x16x32_bf16 v[12:15], v[168:171], v[224:227], v[12:15]
	v_mfma_f32_16x16x32_bf16 v[8:11], v[176:179], v[224:227], v[8:11]
	v_mfma_f32_16x16x32_bf16 v[52:55], v[180:183], v[196:199], v[52:55]
	v_mfma_f32_16x16x32_bf16 v[48:51], v[188:191], v[196:199], v[48:51]
	v_mfma_f32_16x16x32_bf16 v[36:39], v[180:183], v[204:207], v[36:39]
	v_mfma_f32_16x16x32_bf16 v[32:35], v[188:191], v[204:207], v[32:35]
	v_mfma_f32_16x16x32_bf16 v[20:23], v[180:183], v[212:215], v[20:23]
	v_mfma_f32_16x16x32_bf16 v[16:19], v[188:191], v[212:215], v[16:19]
	v_mfma_f32_16x16x32_bf16 v[4:7], v[180:183], v[220:223], v[4:7]
	v_mfma_f32_16x16x32_bf16 v[0:3], v[188:191], v[220:223], v[0:3]
	v_mfma_f32_16x16x32_bf16 v[52:55], v[184:187], v[200:203], v[52:55]
	v_mfma_f32_16x16x32_bf16 v[48:51], v[192:195], v[200:203], v[48:51]
	v_mfma_f32_16x16x32_bf16 v[36:39], v[184:187], v[208:211], v[36:39]
	v_mfma_f32_16x16x32_bf16 v[32:35], v[192:195], v[208:211], v[32:35]
	v_mfma_f32_16x16x32_bf16 v[20:23], v[184:187], v[216:219], v[20:23]
	v_mfma_f32_16x16x32_bf16 v[16:19], v[192:195], v[216:219], v[16:19]
	v_mfma_f32_16x16x32_bf16 v[4:7], v[184:187], v[224:227], v[4:7]
	v_mfma_f32_16x16x32_bf16 v[0:3], v[192:195], v[224:227], v[0:3]
	s_barrier
	s_add_i32 s37, 0, 0x18000
	v_add_u32_e32 v144, s37, v151
	s_add_i32 s91, 0, 0x1c000
	ds_read_b128 v[140:143], v144
	ds_read_b128 v[168:171], v144 offset:1024
	ds_read_b128 v[172:175], v144 offset:2048
	ds_read_b128 v[176:179], v144 offset:3072
	v_add_u32_e32 v144, s91, v151
	ds_read_b128 v[180:183], v144
	ds_read_b128 v[184:187], v144 offset:1024
	ds_read_b128 v[188:191], v144 offset:2048
	ds_read_b128 v[192:195], v144 offset:3072
	s_add_u32 s2, s6, s10
	s_addc_u32 s3, s7, s11
	s_mov_b32 m0, s45
	v_lshl_add_u64 v[242:243], s[2:3], 0, v[132:133]
	ds_read_b128 v[196:199], v167 offset:32768
	ds_read_b128 v[200:203], v167 offset:33792
	ds_read_b128 v[204:207], v167 offset:34816
	ds_read_b128 v[208:211], v167 offset:35840
	ds_read_b128 v[212:215], v167 offset:36864
	ds_read_b128 v[216:219], v167 offset:37888
	ds_read_b128 v[220:223], v167 offset:38912
	ds_read_b128 v[224:227], v167 offset:39936
	global_load_lds_dwordx4 v[242:243], off
	v_lshl_add_u64 v[242:243], s[2:3], 0, v[130:131]
	s_mov_b32 m0, s46
	s_nop 0
	global_load_lds_dwordx4 v[242:243], off
	s_waitcnt vmcnt(8)
	s_waitcnt lgkmcnt(0)
	s_barrier
	s_waitcnt lgkmcnt(0)
	v_mfma_f32_16x16x32_bf16 v[124:127], v[140:143], v[196:199], v[124:127]
	v_mfma_f32_16x16x32_bf16 v[120:123], v[172:175], v[196:199], v[120:123]
	v_mfma_f32_16x16x32_bf16 v[108:111], v[140:143], v[204:207], v[108:111]
	v_mfma_f32_16x16x32_bf16 v[104:107], v[172:175], v[204:207], v[104:107]
	v_mfma_f32_16x16x32_bf16 v[92:95], v[140:143], v[212:215], v[92:95]
	v_mfma_f32_16x16x32_bf16 v[88:91], v[172:175], v[212:215], v[88:91]
	v_mfma_f32_16x16x32_bf16 v[76:79], v[140:143], v[220:223], v[76:79]
	v_mfma_f32_16x16x32_bf16 v[72:75], v[172:175], v[220:223], v[72:75]
	v_mfma_f32_16x16x32_bf16 v[124:127], v[168:171], v[200:203], v[124:127]
	v_mfma_f32_16x16x32_bf16 v[120:123], v[176:179], v[200:203], v[120:123]
	v_mfma_f32_16x16x32_bf16 v[108:111], v[168:171], v[208:211], v[108:111]
	v_mfma_f32_16x16x32_bf16 v[104:107], v[176:179], v[208:211], v[104:107]
	v_mfma_f32_16x16x32_bf16 v[92:95], v[168:171], v[216:219], v[92:95]
	v_mfma_f32_16x16x32_bf16 v[88:91], v[176:179], v[216:219], v[88:91]
	v_mfma_f32_16x16x32_bf16 v[76:79], v[168:171], v[224:227], v[76:79]
	v_mfma_f32_16x16x32_bf16 v[72:75], v[176:179], v[224:227], v[72:75]
	v_mfma_f32_16x16x32_bf16 v[116:119], v[180:183], v[196:199], v[116:119]
	v_mfma_f32_16x16x32_bf16 v[112:115], v[188:191], v[196:199], v[112:115]
	v_mfma_f32_16x16x32_bf16 v[100:103], v[180:183], v[204:207], v[100:103]
	v_mfma_f32_16x16x32_bf16 v[96:99], v[188:191], v[204:207], v[96:99]
	v_mfma_f32_16x16x32_bf16 v[84:87], v[180:183], v[212:215], v[84:87]
	v_mfma_f32_16x16x32_bf16 v[80:83], v[188:191], v[212:215], v[80:83]
	v_mfma_f32_16x16x32_bf16 v[68:71], v[180:183], v[220:223], v[68:71]
	v_mfma_f32_16x16x32_bf16 v[64:67], v[188:191], v[220:223], v[64:67]
	v_mfma_f32_16x16x32_bf16 v[116:119], v[184:187], v[200:203], v[116:119]
	v_mfma_f32_16x16x32_bf16 v[112:115], v[192:195], v[200:203], v[112:115]
	v_mfma_f32_16x16x32_bf16 v[100:103], v[184:187], v[208:211], v[100:103]
	v_mfma_f32_16x16x32_bf16 v[96:99], v[192:195], v[208:211], v[96:99]
	v_mfma_f32_16x16x32_bf16 v[84:87], v[184:187], v[216:219], v[84:87]
	v_mfma_f32_16x16x32_bf16 v[80:83], v[192:195], v[216:219], v[80:83]
	v_mfma_f32_16x16x32_bf16 v[68:71], v[184:187], v[224:227], v[68:71]
	v_mfma_f32_16x16x32_bf16 v[64:67], v[192:195], v[224:227], v[64:67]
	s_barrier
; #define PG8_STAGE(bufoff, gbase, voff) do { _Pragma("unroll") for (int _i = 0; _i < 2; ++_i) \
;         __builtin_amdgcn_global_load_lds((const unsigned*)((const char*)(gbase) + (voff)[_i]), (PG8_LAS unsigned*)(lds + (bufoff) + ldsw + _i * 8192), 16, 0, 0); } while (0)
; #define PG8_LDA(dst, b, h) do { _Pragma("unroll") for (int m = 0; m < 4; ++m) _Pragma("unroll") for (int k = 0; k < 2; ++k) dst[m][k] = *(const PG8_LAS bf16x8*)(lds + PG8_SA(b, h) + aoff + m * 2048 + k * 1024); } while (0)
; #define PG8_MMA(ai, bj, At, Bt) do { __builtin_amdgcn_s_setprio(1); _Pragma("unroll") for (int m = 0; m < 4; ++m) _Pragma("unroll") for (int n = 0; n < 2; ++n) _Pragma("unroll") for (int k = 0; k < 2; ++k) \
;         acc[ai][bj][m][n] = __builtin_amdgcn_mfma_f32_16x16x32_bf16(Bt[n][k], At[m][k], acc[ai][bj][m][n], 0, 0, 0); __builtin_amdgcn_s_setprio(0); } while (0)
; #define PG8_WAIT_V(n) asm volatile("s_waitcnt vmcnt(" #n ")" ::: "memory")
; #define PG8_WAIT_L(n) asm volatile("s_waitcnt lgkmcnt(" #n ")" ::: "memory")
; #define PG8_BAR __builtin_amdgcn_s_barrier()
; #define PG8_SCHED __builtin_amdgcn_sched_barrier(0)
; template <class Epi, class Sched, bool ALIGN_EPI = false, bool SP2 = false>
; __device__ __forceinline__ void gemm_phase(PG8_LAS unsigned char* lds, const Gemm g, const Sched& S, const Epi& E, int tid_in) {
;     ...
;             PG8_LDA(At, 1, 1); PG8_STAGE(PG8_SB(1, 0), b3, voffB); PG8_STAGE(PG8_SB(1, 1), b3 + hstep, voffB); PG8_STAGE(PG8_SA(1, 0), a3, voffA);
;             PG8_WAIT_V(8); PG8_WAIT_L(0); PG8_BAR; PG8_MMA(1, 0, At, B0); PG8_MMA(1, 1, At, B1); PG8_BAR; PG8_SCHED;
	s_add_i32 s2, s37, s42
	v_lshl_add_u64 v[146:147], v[146:147], 0, s[64:65]
	s_mov_b32 m0, s2
	ds_read_b128 v[196:199], v167 offset:49152
	ds_read_b128 v[200:203], v167 offset:50176
	ds_read_b128 v[204:207], v167 offset:51200
	ds_read_b128 v[208:211], v167 offset:52224
	ds_read_b128 v[212:215], v167 offset:53248
	ds_read_b128 v[216:219], v167 offset:54272
	ds_read_b128 v[220:223], v167 offset:55296
	ds_read_b128 v[224:227], v167 offset:56320
	global_load_lds_dwordx4 v[146:147], off
	v_lshl_add_u64 v[146:147], v[162:163], 0, s[64:65]
	s_add_i32 m0, s2, 0x2000
	s_add_i32 s2, s91, s42
	global_load_lds_dwordx4 v[146:147], off
	v_lshl_add_u64 v[146:147], v[228:229], 0, s[64:65]
	s_mov_b32 m0, s2
	s_nop 0
	global_load_lds_dwordx4 v[146:147], off
	v_lshl_add_u64 v[146:147], v[230:231], 0, s[64:65]
	s_add_i32 m0, s2, 0x2000
	s_nop 0
	global_load_lds_dwordx4 v[146:147], off
	v_lshl_add_u64 v[146:147], v[238:239], 0, s[64:65]
	s_mov_b32 m0, s56
	s_nop 0
	global_load_lds_dwordx4 v[146:147], off
	v_lshl_add_u64 v[146:147], v[240:241], 0, s[64:65]
	s_mov_b32 m0, s57
	s_nop 0
	global_load_lds_dwordx4 v[146:147], off
	s_waitcnt vmcnt(8)
	s_waitcnt lgkmcnt(0)
	s_barrier
	s_waitcnt lgkmcnt(0)
	v_mfma_f32_16x16x32_bf16 v[60:63], v[140:143], v[196:199], v[60:63]
	v_mfma_f32_16x16x32_bf16 v[56:59], v[172:175], v[196:199], v[56:59]
	v_mfma_f32_16x16x32_bf16 v[44:47], v[140:143], v[204:207], v[44:47]
	v_mfma_f32_16x16x32_bf16 v[40:43], v[172:175], v[204:207], v[40:43]
	v_mfma_f32_16x16x32_bf16 v[28:31], v[140:143], v[212:215], v[28:31]
	v_mfma_f32_16x16x32_bf16 v[24:27], v[172:175], v[212:215], v[24:27]
	v_mfma_f32_16x16x32_bf16 v[12:15], v[140:143], v[220:223], v[12:15]
	v_mfma_f32_16x16x32_bf16 v[8:11], v[172:175], v[220:223], v[8:11]
	v_mfma_f32_16x16x32_bf16 v[60:63], v[168:171], v[200:203], v[60:63]
	v_mfma_f32_16x16x32_bf16 v[56:59], v[176:179], v[200:203], v[56:59]
	v_mfma_f32_16x16x32_bf16 v[44:47], v[168:171], v[208:211], v[44:47]
	v_mfma_f32_16x16x32_bf16 v[40:43], v[176:179], v[208:211], v[40:43]
	v_mfma_f32_16x16x32_bf16 v[28:31], v[168:171], v[216:219], v[28:31]
	v_mfma_f32_16x16x32_bf16 v[24:27], v[176:179], v[216:219], v[24:27]
	v_mfma_f32_16x16x32_bf16 v[12:15], v[168:171], v[224:227], v[12:15]
	v_mfma_f32_16x16x32_bf16 v[8:11], v[176:179], v[224:227], v[8:11]
	v_mfma_f32_16x16x32_bf16 v[52:55], v[180:183], v[196:199], v[52:55]
	v_mfma_f32_16x16x32_bf16 v[48:51], v[188:191], v[196:199], v[48:51]
	v_mfma_f32_16x16x32_bf16 v[36:39], v[180:183], v[204:207], v[36:39]
	v_mfma_f32_16x16x32_bf16 v[32:35], v[188:191], v[204:207], v[32:35]
	v_mfma_f32_16x16x32_bf16 v[20:23], v[180:183], v[212:215], v[20:23]
	v_mfma_f32_16x16x32_bf16 v[16:19], v[188:191], v[212:215], v[16:19]
	v_mfma_f32_16x16x32_bf16 v[4:7], v[180:183], v[220:223], v[4:7]
	v_mfma_f32_16x16x32_bf16 v[0:3], v[188:191], v[220:223], v[0:3]
	v_mfma_f32_16x16x32_bf16 v[52:55], v[184:187], v[200:203], v[52:55]
	v_mfma_f32_16x16x32_bf16 v[48:51], v[192:195], v[200:203], v[48:51]
	v_mfma_f32_16x16x32_bf16 v[36:39], v[184:187], v[208:211], v[36:39]
	v_mfma_f32_16x16x32_bf16 v[32:35], v[192:195], v[208:211], v[32:35]
	v_mfma_f32_16x16x32_bf16 v[20:23], v[184:187], v[216:219], v[20:23]
	v_mfma_f32_16x16x32_bf16 v[16:19], v[192:195], v[216:219], v[16:19]
	v_mfma_f32_16x16x32_bf16 v[4:7], v[184:187], v[224:227], v[4:7]
	v_mfma_f32_16x16x32_bf16 v[0:3], v[192:195], v[224:227], v[0:3]
	s_barrier
	s_add_u32 s0, s0, 0x100
	s_addc_u32 s1, s1, 0
	s_add_u32 s22, s22, 0x100
	s_addc_u32 s23, s23, 0
	s_cmp_ge_i32 s36, s52
	s_mov_b32 s6, s36
	s_cbranch_scc0 .LBB0_928

; #define PG8_STAGE(bufoff, gbase, voff) do { _Pragma("unroll") for (int _i = 0; _i < 2; ++_i) \
;         __builtin_amdgcn_global_load_lds((const unsigned*)((const char*)(gbase) + (voff)[_i]), (PG8_LAS unsigned*)(lds + (bufoff) + ldsw + _i * 8192), 16, 0, 0); } while (0)
; #define PG8_LDA(dst, b, h) do { _Pragma("unroll") for (int m = 0; m < 4; ++m) _Pragma("unroll") for (int k = 0; k < 2; ++k) dst[m][k] = *(const PG8_LAS bf16x8*)(lds + PG8_SA(b, h) + aoff + m * 2048 + k * 1024); } while (0)
; #define PG8_LDB(dst, b, h) do { _Pragma("unroll") for (int n = 0; n < 2; ++n) _Pragma("unroll") for (int k = 0; k < 2; ++k) dst[n][k] = *(const PG8_LAS bf16x8*)(lds + PG8_SB(b, h) + boff + n * 2048 + k * 1024); } while (0)
; #define PG8_MMA(ai, bj, At, Bt) do { __builtin_amdgcn_s_setprio(1); _Pragma("unroll") for (int m = 0; m < 4; ++m) _Pragma("unroll") for (int n = 0; n < 2; ++n) _Pragma("unroll") for (int k = 0; k < 2; ++k) \
;         acc[ai][bj][m][n] = __builtin_amdgcn_mfma_f32_16x16x32_bf16(Bt[n][k], At[m][k], acc[ai][bj][m][n], 0, 0, 0); __builtin_amdgcn_s_setprio(0); } while (0)
; #define PG8_WAIT_V(n) asm volatile("s_waitcnt vmcnt(" #n ")" ::: "memory")
; #define PG8_WAIT_L(n) asm volatile("s_waitcnt lgkmcnt(" #n ")" ::: "memory")
; #define PG8_BAR __builtin_amdgcn_s_barrier()
; #define PG8_SCHED __builtin_amdgcn_sched_barrier(0)
; template <class Epi, class Sched, bool ALIGN_EPI = false, bool SP2 = false>
; __device__ __forceinline__ void gemm_phase(PG8_LAS unsigned char* lds, const Gemm g, const Sched& S, const Epi& E, int tid_in) {
;     ...
;             const bool last = (t == nt - 2);
;             const char* a1 = cA + (size_t)(t + 1) * kstep;
;             const char* a2 = last ? nA : cA + (size_t)(t + 2) * kstep; const char* b2 = last ? nB : cB + (size_t)(t + 2) * kstep;
;             const char* a3 = a2 + kstep; const char* b3 = b2 + kstep;
;             if (last && has_next) S.a_ready(nxt);
;             if constexpr (SP2) {
;             PG8_LDB(B0, 0, 0); PG8_LDB(B1, 0, 1); PG8_SCHED; PG8_LDA(At, 0, 0); PG8_STAGE(PG8_SA(1, 1), a1 + hstep, voffA);
;             PG8_WAIT_V(8); PG8_WAIT_L(0); PG8_BAR; PG8_MMA(0, 0, At, B0); PG8_MMA(0, 1, At, B1); PG8_BAR; PG8_SCHED;
;             PG8_LDA(At, 0, 1); PG8_STAGE(PG8_SB(0, 0), b2, voffB); PG8_STAGE(PG8_SB(0, 1), b2 + hstep, voffB); PG8_STAGE(PG8_SA(0, 0), a2, voffA);
.LBB0_1024:
	s_add_i32 s36, s22, 2
	s_add_u32 s37, s0, 0x80
	s_addc_u32 s23, s1, 0
	s_add_i32 s93, 0, 0x10000
	s_cmp_eq_u32 s88, s22
	s_cselect_b32 s23, s7, s23
	s_cselect_b32 s22, s6, s37
	s_cselect_b32 vcc_hi, s45, s92
	s_cselect_b32 vcc_lo, s44, s55
	s_add_i32 s37, 0, 0x14000
	v_add_u32_e32 v146, s93, v237
	v_add_u32_e32 v154, s37, v237
	ds_read_b128 v[134:137], v146
	ds_read_b128 v[138:141], v146 offset:1024
	ds_read_b128 v[142:145], v146 offset:2048
	ds_read_b128 v[146:149], v146 offset:3072
	ds_read_b128 v[150:153], v154
	ds_read_b128 v[166:169], v154 offset:1024
	ds_read_b128 v[170:173], v154 offset:2048
	ds_read_b128 v[174:177], v154 offset:3072
	v_lshl_add_u64 v[154:155], s[0:1], 0, v[130:131]
	s_add_i32 m0, s47, 0xc000
	ds_read_b128 v[178:181], v241
	ds_read_b128 v[182:185], v241 offset:1024
	ds_read_b128 v[186:189], v241 offset:2048
	ds_read_b128 v[190:193], v241 offset:3072
	ds_read_b128 v[194:197], v241 offset:4096
	ds_read_b128 v[198:201], v241 offset:5120
	ds_read_b128 v[202:205], v241 offset:6144
	ds_read_b128 v[206:209], v241 offset:7168
	global_load_lds_dwordx4 v[154:155], off
	v_lshl_add_u64 v[154:155], s[0:1], 0, v[132:133]
	s_add_i32 m0, s47, 0xe000
	s_nop 0
	global_load_lds_dwordx4 v[154:155], off
	s_waitcnt vmcnt(8)
	s_waitcnt lgkmcnt(0)
	s_barrier
	s_waitcnt lgkmcnt(0)
	v_mfma_f32_16x16x32_bf16 v[124:127], v[134:137], v[178:181], v[124:127]
	v_mfma_f32_16x16x32_bf16 v[120:123], v[142:145], v[178:181], v[120:123]
	v_mfma_f32_16x16x32_bf16 v[108:111], v[134:137], v[186:189], v[108:111]
	v_mfma_f32_16x16x32_bf16 v[104:107], v[142:145], v[186:189], v[104:107]
	v_mfma_f32_16x16x32_bf16 v[92:95], v[134:137], v[194:197], v[92:95]
	v_mfma_f32_16x16x32_bf16 v[88:91], v[142:145], v[194:197], v[88:91]
	v_mfma_f32_16x16x32_bf16 v[76:79], v[134:137], v[202:205], v[76:79]
	v_mfma_f32_16x16x32_bf16 v[72:75], v[142:145], v[202:205], v[72:75]
	v_mfma_f32_16x16x32_bf16 v[124:127], v[138:141], v[182:185], v[124:127]
	v_mfma_f32_16x16x32_bf16 v[120:123], v[146:149], v[182:185], v[120:123]
	v_mfma_f32_16x16x32_bf16 v[108:111], v[138:141], v[190:193], v[108:111]
	v_mfma_f32_16x16x32_bf16 v[104:107], v[146:149], v[190:193], v[104:107]
	v_mfma_f32_16x16x32_bf16 v[92:95], v[138:141], v[198:201], v[92:95]
	v_mfma_f32_16x16x32_bf16 v[88:91], v[146:149], v[198:201], v[88:91]
	v_mfma_f32_16x16x32_bf16 v[76:79], v[138:141], v[206:209], v[76:79]
	v_mfma_f32_16x16x32_bf16 v[72:75], v[146:149], v[206:209], v[72:75]
	v_mfma_f32_16x16x32_bf16 v[116:119], v[150:153], v[178:181], v[116:119]
	v_mfma_f32_16x16x32_bf16 v[112:115], v[170:173], v[178:181], v[112:115]
	v_mfma_f32_16x16x32_bf16 v[100:103], v[150:153], v[186:189], v[100:103]
	v_mfma_f32_16x16x32_bf16 v[96:99], v[170:173], v[186:189], v[96:99]
	v_mfma_f32_16x16x32_bf16 v[84:87], v[150:153], v[194:197], v[84:87]
	v_mfma_f32_16x16x32_bf16 v[80:83], v[170:173], v[194:197], v[80:83]
	v_mfma_f32_16x16x32_bf16 v[68:71], v[150:153], v[202:205], v[68:71]
	v_mfma_f32_16x16x32_bf16 v[64:67], v[170:173], v[202:205], v[64:67]
	v_mfma_f32_16x16x32_bf16 v[116:119], v[166:169], v[182:185], v[116:119]
	v_mfma_f32_16x16x32_bf16 v[112:115], v[174:177], v[182:185], v[112:115]
	v_mfma_f32_16x16x32_bf16 v[100:103], v[166:169], v[190:193], v[100:103]
	v_mfma_f32_16x16x32_bf16 v[96:99], v[174:177], v[190:193], v[96:99]
	v_mfma_f32_16x16x32_bf16 v[84:87], v[166:169], v[198:201], v[84:87]
	v_mfma_f32_16x16x32_bf16 v[80:83], v[174:177], v[198:201], v[80:83]
	v_mfma_f32_16x16x32_bf16 v[68:71], v[166:169], v[206:209], v[68:71]
	v_mfma_f32_16x16x32_bf16 v[64:67], v[174:177], v[206:209], v[64:67]
	s_barrier
	s_add_i32 s93, s93, s46
	v_lshl_add_u64 v[154:155], vcc, 0, v[156:157]
	s_mov_b32 m0, s93
	ds_read_b128 v[178:181], v241 offset:16384
	ds_read_b128 v[182:185], v241 offset:17408
	ds_read_b128 v[186:189], v241 offset:18432
	ds_read_b128 v[190:193], v241 offset:19456
	ds_read_b128 v[194:197], v241 offset:20480
	ds_read_b128 v[198:201], v241 offset:21504
	ds_read_b128 v[202:205], v241 offset:22528
	ds_read_b128 v[206:209], v241 offset:23552
	global_load_lds_dwordx4 v[154:155], off
	s_add_i32 m0, s93, 0x2000
	v_lshl_add_u64 v[162:163], vcc, 0, v[128:129]
	s_add_u32 vcc_lo, vcc_lo, s10
	s_addc_u32 vcc_hi, vcc_hi, s11
	s_add_i32 s37, s37, s46
	global_load_lds_dwordx4 v[162:163], off
	v_lshl_add_u64 v[210:211], vcc, 0, v[156:157]
	s_mov_b32 m0, s37
	v_lshl_add_u64 v[212:213], vcc, 0, v[128:129]
	global_load_lds_dwordx4 v[210:211], off
	s_add_i32 m0, s37, 0x2000
	v_lshl_add_u64 v[214:215], s[22:23], 0, v[156:157]
	global_load_lds_dwordx4 v[212:213], off
	s_mov_b32 m0, s47
	v_lshl_add_u64 v[216:217], s[22:23], 0, v[128:129]
	global_load_lds_dwordx4 v[214:215], off
	s_mov_b32 m0, s52
	s_nop 0
	global_load_lds_dwordx4 v[216:217], off
	s_waitcnt vmcnt(8)
	s_waitcnt lgkmcnt(0)
	s_barrier
; #define PG8_STAGE(bufoff, gbase, voff) do { _Pragma("unroll") for (int _i = 0; _i < 2; ++_i) \
;         __builtin_amdgcn_global_load_lds((const unsigned*)((const char*)(gbase) + (voff)[_i]), (PG8_LAS unsigned*)(lds + (bufoff) + ldsw + _i * 8192), 16, 0, 0); } while (0)
; #define PG8_LDA(dst, b, h) do { _Pragma("unroll") for (int m = 0; m < 4; ++m) _Pragma("unroll") for (int k = 0; k < 2; ++k) dst[m][k] = *(const PG8_LAS bf16x8*)(lds + PG8_SA(b, h) + aoff + m * 2048 + k * 1024); } while (0)
; #define PG8_LDB(dst, b, h) do { _Pragma("unroll") for (int n = 0; n < 2; ++n) _Pragma("unroll") for (int k = 0; k < 2; ++k) dst[n][k] = *(const PG8_LAS bf16x8*)(lds + PG8_SB(b, h) + boff + n * 2048 + k * 1024); } while (0)
; #define PG8_MMA(ai, bj, At, Bt) do { __builtin_amdgcn_s_setprio(1); _Pragma("unroll") for (int m = 0; m < 4; ++m) _Pragma("unroll") for (int n = 0; n < 2; ++n) _Pragma("unroll") for (int k = 0; k < 2; ++k) \
;         acc[ai][bj][m][n] = __builtin_amdgcn_mfma_f32_16x16x32_bf16(Bt[n][k], At[m][k], acc[ai][bj][m][n], 0, 0, 0); __builtin_amdgcn_s_setprio(0); } while (0)
; #define PG8_WAIT_V(n) asm volatile("s_waitcnt vmcnt(" #n ")" ::: "memory")
; #define PG8_WAIT_L(n) asm volatile("s_waitcnt lgkmcnt(" #n ")" ::: "memory")
; #define PG8_BAR __builtin_amdgcn_s_barrier()
; #define PG8_SCHED __builtin_amdgcn_sched_barrier(0)
; template <class Epi, class Sched, bool ALIGN_EPI = false, bool SP2 = false>
; __device__ __forceinline__ void gemm_phase(PG8_LAS unsigned char* lds, const Gemm g, const Sched& S, const Epi& E, int tid_in) {
;     ...
;             PG8_WAIT_V(8); PG8_WAIT_L(0); PG8_BAR; PG8_MMA(1, 0, At, B0); PG8_MMA(1, 1, At, B1); PG8_BAR; PG8_SCHED;
;             PG8_LDB(B0, 1, 0); PG8_LDB(B1, 1, 1); PG8_SCHED; PG8_LDA(At, 1, 0); PG8_STAGE(PG8_SA(0, 1), a2 + hstep, voffA);
;             PG8_WAIT_V(8); PG8_WAIT_L(0); PG8_BAR; PG8_MMA(0, 0, At, B0); PG8_MMA(0, 1, At, B1); PG8_BAR; PG8_SCHED;
	s_waitcnt lgkmcnt(0)
	v_mfma_f32_16x16x32_bf16 v[60:63], v[134:137], v[178:181], v[60:63]
	v_mfma_f32_16x16x32_bf16 v[56:59], v[142:145], v[178:181], v[56:59]
	v_mfma_f32_16x16x32_bf16 v[44:47], v[134:137], v[186:189], v[44:47]
	v_mfma_f32_16x16x32_bf16 v[40:43], v[142:145], v[186:189], v[40:43]
	v_mfma_f32_16x16x32_bf16 v[28:31], v[134:137], v[194:197], v[28:31]
	v_mfma_f32_16x16x32_bf16 v[24:27], v[142:145], v[194:197], v[24:27]
	v_mfma_f32_16x16x32_bf16 v[12:15], v[134:137], v[202:205], v[12:15]
	v_mfma_f32_16x16x32_bf16 v[8:11], v[142:145], v[202:205], v[8:11]
	v_mfma_f32_16x16x32_bf16 v[60:63], v[138:141], v[182:185], v[60:63]
	v_mfma_f32_16x16x32_bf16 v[56:59], v[146:149], v[182:185], v[56:59]
	v_mfma_f32_16x16x32_bf16 v[44:47], v[138:141], v[190:193], v[44:47]
	v_mfma_f32_16x16x32_bf16 v[40:43], v[146:149], v[190:193], v[40:43]
	v_mfma_f32_16x16x32_bf16 v[28:31], v[138:141], v[198:201], v[28:31]
	v_mfma_f32_16x16x32_bf16 v[24:27], v[146:149], v[198:201], v[24:27]
	v_mfma_f32_16x16x32_bf16 v[12:15], v[138:141], v[206:209], v[12:15]
	v_mfma_f32_16x16x32_bf16 v[8:11], v[146:149], v[206:209], v[8:11]
	v_mfma_f32_16x16x32_bf16 v[52:55], v[150:153], v[178:181], v[52:55]
	v_mfma_f32_16x16x32_bf16 v[48:51], v[170:173], v[178:181], v[48:51]
	v_mfma_f32_16x16x32_bf16 v[36:39], v[150:153], v[186:189], v[36:39]
	v_mfma_f32_16x16x32_bf16 v[32:35], v[170:173], v[186:189], v[32:35]
	v_mfma_f32_16x16x32_bf16 v[20:23], v[150:153], v[194:197], v[20:23]
	v_mfma_f32_16x16x32_bf16 v[16:19], v[170:173], v[194:197], v[16:19]
	v_mfma_f32_16x16x32_bf16 v[4:7], v[150:153], v[202:205], v[4:7]
	v_mfma_f32_16x16x32_bf16 v[0:3], v[170:173], v[202:205], v[0:3]
	v_mfma_f32_16x16x32_bf16 v[52:55], v[166:169], v[182:185], v[52:55]
	v_mfma_f32_16x16x32_bf16 v[48:51], v[174:177], v[182:185], v[48:51]
	v_mfma_f32_16x16x32_bf16 v[36:39], v[166:169], v[190:193], v[36:39]
	v_mfma_f32_16x16x32_bf16 v[32:35], v[174:177], v[190:193], v[32:35]
	v_mfma_f32_16x16x32_bf16 v[20:23], v[166:169], v[198:201], v[20:23]
	v_mfma_f32_16x16x32_bf16 v[16:19], v[174:177], v[198:201], v[16:19]
	v_mfma_f32_16x16x32_bf16 v[4:7], v[166:169], v[206:209], v[4:7]
	v_mfma_f32_16x16x32_bf16 v[0:3], v[174:177], v[206:209], v[0:3]
	s_barrier
	s_add_i32 s37, 0, 0x18000
	s_add_i32 s93, 0, 0x1c000
	v_add_u32_e32 v146, s37, v237
	v_add_u32_e32 v174, s93, v237
	ds_read_b128 v[134:137], v146
	ds_read_b128 v[138:141], v146 offset:1024
	ds_read_b128 v[142:145], v146 offset:2048
	ds_read_b128 v[146:149], v146 offset:3072
	ds_read_b128 v[150:153], v174
	ds_read_b128 v[166:169], v174 offset:1024
	ds_read_b128 v[170:173], v174 offset:2048
	ds_read_b128 v[174:177], v174 offset:3072
	s_add_u32 s22, s22, s10
	s_addc_u32 s23, s23, s11
	s_mov_b32 m0, s53
	v_lshl_add_u64 v[218:219], s[22:23], 0, v[156:157]
	ds_read_b128 v[178:181], v241 offset:32768
	ds_read_b128 v[182:185], v241 offset:33792
	ds_read_b128 v[186:189], v241 offset:34816
	ds_read_b128 v[190:193], v241 offset:35840
	ds_read_b128 v[194:197], v241 offset:36864
	ds_read_b128 v[198:201], v241 offset:37888
	ds_read_b128 v[202:205], v241 offset:38912
	ds_read_b128 v[206:209], v241 offset:39936
	global_load_lds_dwordx4 v[218:219], off
	v_lshl_add_u64 v[218:219], s[22:23], 0, v[128:129]
	s_mov_b32 m0, s56
	s_nop 0
	global_load_lds_dwordx4 v[218:219], off
	s_waitcnt vmcnt(8)
	s_waitcnt lgkmcnt(0)
	s_barrier
	s_waitcnt lgkmcnt(0)
	v_mfma_f32_16x16x32_bf16 v[124:127], v[134:137], v[178:181], v[124:127]
	v_mfma_f32_16x16x32_bf16 v[120:123], v[142:145], v[178:181], v[120:123]
	v_mfma_f32_16x16x32_bf16 v[108:111], v[134:137], v[186:189], v[108:111]
	v_mfma_f32_16x16x32_bf16 v[104:107], v[142:145], v[186:189], v[104:107]
	v_mfma_f32_16x16x32_bf16 v[92:95], v[134:137], v[194:197], v[92:95]
	v_mfma_f32_16x16x32_bf16 v[88:91], v[142:145], v[194:197], v[88:91]
	v_mfma_f32_16x16x32_bf16 v[76:79], v[134:137], v[202:205], v[76:79]
	v_mfma_f32_16x16x32_bf16 v[72:75], v[142:145], v[202:205], v[72:75]
	v_mfma_f32_16x16x32_bf16 v[124:127], v[138:141], v[182:185], v[124:127]
	v_mfma_f32_16x16x32_bf16 v[120:123], v[146:149], v[182:185], v[120:123]
	v_mfma_f32_16x16x32_bf16 v[108:111], v[138:141], v[190:193], v[108:111]
	v_mfma_f32_16x16x32_bf16 v[104:107], v[146:149], v[190:193], v[104:107]
	v_mfma_f32_16x16x32_bf16 v[92:95], v[138:141], v[198:201], v[92:95]
	v_mfma_f32_16x16x32_bf16 v[88:91], v[146:149], v[198:201], v[88:91]
	v_mfma_f32_16x16x32_bf16 v[76:79], v[138:141], v[206:209], v[76:79]
	v_mfma_f32_16x16x32_bf16 v[72:75], v[146:149], v[206:209], v[72:75]
	v_mfma_f32_16x16x32_bf16 v[116:119], v[150:153], v[178:181], v[116:119]
	v_mfma_f32_16x16x32_bf16 v[112:115], v[170:173], v[178:181], v[112:115]
	v_mfma_f32_16x16x32_bf16 v[100:103], v[150:153], v[186:189], v[100:103]
	v_mfma_f32_16x16x32_bf16 v[96:99], v[170:173], v[186:189], v[96:99]
	v_mfma_f32_16x16x32_bf16 v[84:87], v[150:153], v[194:197], v[84:87]
	v_mfma_f32_16x16x32_bf16 v[80:83], v[170:173], v[194:197], v[80:83]
	v_mfma_f32_16x16x32_bf16 v[68:71], v[150:153], v[202:205], v[68:71]
	v_mfma_f32_16x16x32_bf16 v[64:67], v[170:173], v[202:205], v[64:67]
	v_mfma_f32_16x16x32_bf16 v[116:119], v[166:169], v[182:185], v[116:119]
	v_mfma_f32_16x16x32_bf16 v[112:115], v[174:177], v[182:185], v[112:115]
	v_mfma_f32_16x16x32_bf16 v[100:103], v[166:169], v[190:193], v[100:103]
	v_mfma_f32_16x16x32_bf16 v[96:99], v[174:177], v[190:193], v[96:99]
	v_mfma_f32_16x16x32_bf16 v[84:87], v[166:169], v[198:201], v[84:87]
	v_mfma_f32_16x16x32_bf16 v[80:83], v[174:177], v[198:201], v[80:83]
	v_mfma_f32_16x16x32_bf16 v[68:71], v[166:169], v[206:209], v[68:71]
	v_mfma_f32_16x16x32_bf16 v[64:67], v[174:177], v[206:209], v[64:67]
	s_barrier
; #define PG8_STAGE(bufoff, gbase, voff) do { _Pragma("unroll") for (int _i = 0; _i < 2; ++_i) \
;         __builtin_amdgcn_global_load_lds((const unsigned*)((const char*)(gbase) + (voff)[_i]), (PG8_LAS unsigned*)(lds + (bufoff) + ldsw + _i * 8192), 16, 0, 0); } while (0)
; #define PG8_LDA(dst, b, h) do { _Pragma("unroll") for (int m = 0; m < 4; ++m) _Pragma("unroll") for (int k = 0; k < 2; ++k) dst[m][k] = *(const PG8_LAS bf16x8*)(lds + PG8_SA(b, h) + aoff + m * 2048 + k * 1024); } while (0)
; #define PG8_MMA(ai, bj, At, Bt) do { __builtin_amdgcn_s_setprio(1); _Pragma("unroll") for (int m = 0; m < 4; ++m) _Pragma("unroll") for (int n = 0; n < 2; ++n) _Pragma("unroll") for (int k = 0; k < 2; ++k) \
;         acc[ai][bj][m][n] = __builtin_amdgcn_mfma_f32_16x16x32_bf16(Bt[n][k], At[m][k], acc[ai][bj][m][n], 0, 0, 0); __builtin_amdgcn_s_setprio(0); } while (0)
; #define PG8_WAIT_V(n) asm volatile("s_waitcnt vmcnt(" #n ")" ::: "memory")
; #define PG8_WAIT_L(n) asm volatile("s_waitcnt lgkmcnt(" #n ")" ::: "memory")
; #define PG8_BAR __builtin_amdgcn_s_barrier()
; #define PG8_SCHED __builtin_amdgcn_sched_barrier(0)
; template <class Epi, class Sched, bool ALIGN_EPI = false, bool SP2 = false>
; __device__ __forceinline__ void gemm_phase(PG8_LAS unsigned char* lds, const Gemm g, const Sched& S, const Epi& E, int tid_in) {
;     ...
;             PG8_LDA(At, 1, 1); PG8_STAGE(PG8_SB(1, 0), b3, voffB); PG8_STAGE(PG8_SB(1, 1), b3 + hstep, voffB); PG8_STAGE(PG8_SA(1, 0), a3, voffA);
;             PG8_WAIT_V(8); PG8_WAIT_L(0); PG8_BAR; PG8_MMA(1, 0, At, B0); PG8_MMA(1, 1, At, B1); PG8_BAR; PG8_SCHED;
	s_add_i32 s22, s37, s46
	v_lshl_add_u64 v[154:155], v[154:155], 0, s[64:65]
	s_mov_b32 m0, s22
	ds_read_b128 v[178:181], v241 offset:49152
	ds_read_b128 v[182:185], v241 offset:50176
	ds_read_b128 v[186:189], v241 offset:51200
	ds_read_b128 v[190:193], v241 offset:52224
	ds_read_b128 v[194:197], v241 offset:53248
	ds_read_b128 v[198:201], v241 offset:54272
	ds_read_b128 v[202:205], v241 offset:55296
	ds_read_b128 v[206:209], v241 offset:56320
	global_load_lds_dwordx4 v[154:155], off
	v_lshl_add_u64 v[154:155], v[162:163], 0, s[64:65]
	s_add_i32 m0, s22, 0x2000
	s_add_i32 s22, s93, s46
	global_load_lds_dwordx4 v[154:155], off
	v_lshl_add_u64 v[154:155], v[210:211], 0, s[64:65]
	s_mov_b32 m0, s22
	s_nop 0
	global_load_lds_dwordx4 v[154:155], off
	v_lshl_add_u64 v[154:155], v[212:213], 0, s[64:65]
	s_add_i32 m0, s22, 0x2000
	s_nop 0
	global_load_lds_dwordx4 v[154:155], off
	v_lshl_add_u64 v[154:155], v[214:215], 0, s[64:65]
	s_mov_b32 m0, s66
	s_nop 0
	global_load_lds_dwordx4 v[154:155], off
	v_lshl_add_u64 v[154:155], v[216:217], 0, s[64:65]
	s_mov_b32 m0, s67
	s_nop 0
	global_load_lds_dwordx4 v[154:155], off
	s_waitcnt vmcnt(8)
	s_waitcnt lgkmcnt(0)
	s_barrier
	s_waitcnt lgkmcnt(0)
	v_mfma_f32_16x16x32_bf16 v[60:63], v[134:137], v[178:181], v[60:63]
	v_mfma_f32_16x16x32_bf16 v[56:59], v[142:145], v[178:181], v[56:59]
	v_mfma_f32_16x16x32_bf16 v[44:47], v[134:137], v[186:189], v[44:47]
	v_mfma_f32_16x16x32_bf16 v[40:43], v[142:145], v[186:189], v[40:43]
	v_mfma_f32_16x16x32_bf16 v[28:31], v[134:137], v[194:197], v[28:31]
	v_mfma_f32_16x16x32_bf16 v[24:27], v[142:145], v[194:197], v[24:27]
	v_mfma_f32_16x16x32_bf16 v[12:15], v[134:137], v[202:205], v[12:15]
	v_mfma_f32_16x16x32_bf16 v[8:11], v[142:145], v[202:205], v[8:11]
	v_mfma_f32_16x16x32_bf16 v[60:63], v[138:141], v[182:185], v[60:63]
	v_mfma_f32_16x16x32_bf16 v[56:59], v[146:149], v[182:185], v[56:59]
	v_mfma_f32_16x16x32_bf16 v[44:47], v[138:141], v[190:193], v[44:47]
	v_mfma_f32_16x16x32_bf16 v[40:43], v[146:149], v[190:193], v[40:43]
	v_mfma_f32_16x16x32_bf16 v[28:31], v[138:141], v[198:201], v[28:31]
	v_mfma_f32_16x16x32_bf16 v[24:27], v[146:149], v[198:201], v[24:27]
	v_mfma_f32_16x16x32_bf16 v[12:15], v[138:141], v[206:209], v[12:15]
	v_mfma_f32_16x16x32_bf16 v[8:11], v[146:149], v[206:209], v[8:11]
	v_mfma_f32_16x16x32_bf16 v[52:55], v[150:153], v[178:181], v[52:55]
	v_mfma_f32_16x16x32_bf16 v[48:51], v[170:173], v[178:181], v[48:51]
	v_mfma_f32_16x16x32_bf16 v[36:39], v[150:153], v[186:189], v[36:39]
	v_mfma_f32_16x16x32_bf16 v[32:35], v[170:173], v[186:189], v[32:35]
	v_mfma_f32_16x16x32_bf16 v[20:23], v[150:153], v[194:197], v[20:23]
	v_mfma_f32_16x16x32_bf16 v[16:19], v[170:173], v[194:197], v[16:19]
	v_mfma_f32_16x16x32_bf16 v[4:7], v[150:153], v[202:205], v[4:7]
	v_mfma_f32_16x16x32_bf16 v[0:3], v[170:173], v[202:205], v[0:3]
	v_mfma_f32_16x16x32_bf16 v[52:55], v[166:169], v[182:185], v[52:55]
	v_mfma_f32_16x16x32_bf16 v[48:51], v[174:177], v[182:185], v[48:51]
	v_mfma_f32_16x16x32_bf16 v[36:39], v[166:169], v[190:193], v[36:39]
	v_mfma_f32_16x16x32_bf16 v[32:35], v[174:177], v[190:193], v[32:35]
	v_mfma_f32_16x16x32_bf16 v[20:23], v[166:169], v[198:201], v[20:23]
	v_mfma_f32_16x16x32_bf16 v[16:19], v[174:177], v[198:201], v[16:19]
	v_mfma_f32_16x16x32_bf16 v[4:7], v[166:169], v[206:209], v[4:7]
	v_mfma_f32_16x16x32_bf16 v[0:3], v[174:177], v[206:209], v[0:3]
	s_barrier
	s_add_u32 s0, s0, 0x100
	s_addc_u32 s1, s1, 0
	s_add_u32 s55, s55, 0x100
	s_addc_u32 s92, s92, 0
	s_cmp_ge_i32 s36, s63
	s_mov_b32 s22, s36
	s_cbranch_scc0 .LBB0_1024

; #define PH_END do { ++ph; } while (0)
; #define PH_END do { if (ph >= lo && ph + 1 < hi) { if (ph == 0) { cg::this_grid().sync(); (void)xcd_barrier_post((unsigned*)args.ws, (volatile LAS unsigned*)((LAS unsigned char*)lds_raw + RING_BYTES), MYTID == 0); } else XBAR; } ++ph; } while (0)
; __device__ __forceinline__ void xcd_barrier(const XcdBarrier& b, bool is_t0) {
;     asm volatile("s_waitcnt vmcnt(0)" ::: "memory");
;     __syncthreads();
;     if (is_t0) {
;         unsigned* bar = b.bar;
;         __builtin_amdgcn_s_waitcnt(0);
;         unsigned nloc = b.st[0], nx = b.st[1];
;         if (nloc == 0u) { xcd_barrier_complete(bar, b.x, nloc, nx); b.st[0] = nloc; b.st[1] = nx; }
; __global__ void __launch_bounds__(NTHR, 2) mega_fwd(Args args) {
;     ...
;         if (PH_ON) { MKF; MKT; final_norm(F, T); }
;         PH_END;
.LBB0_1120:
	s_add_i32 s28, s30, 15
	s_cmp_lt_i32 s28, s21
	s_cselect_b64 s[0:1], -1, 0
	s_and_b64 s[2:3], s[4:5], s[0:1]
	s_andn2_b64 vcc, exec, s[2:3]
	s_branch .LBB0_1190
	s_cmp_lg_u32 s8, 0
	s_cbranch_scc0 .LBB0_1133
	s_mov_b32 s2, s61
	s_getreg_b32 s4, hwreg(HW_REG_XCC_ID, 0, 4)
	s_waitcnt vmcnt(0)
	s_waitcnt lgkmcnt(0)
	v_mbcnt_lo_u32_b32 v0, -1, s2
	v_mbcnt_hi_u32_b32 v0, -1, v0
	v_sub_u32_e32 v0, 0, v0
	v_cmp_eq_u32_e32 vcc, s56, v0
	s_barrier
	s_and_saveexec_b64 s[2:3], vcc
	s_cbranch_execz .LBB0_1175
	s_add_i32 s11, 0, 0x20000
	v_mov_b32_e32 v0, s11
	s_waitcnt vmcnt(0) expcnt(0) lgkmcnt(0)
	ds_read_b32 v2, v0
	v_readlane_b32 s5, v254, 50
	s_and_b32 s10, s4, 15
	s_waitcnt lgkmcnt(0)
	v_cmp_ne_u32_e32 vcc, 0, v2
	v_mov_b32_e32 v0, s5
	ds_read_b32 v0, v0
	s_cbranch_vccnz .LBB0_1139
	v_readlane_b32 s6, v254, 17
	v_readlane_b32 s7, v254, 18
	s_load_dwordx2 s[4:5], s[6:7], 0x0
	s_nop 0
	s_load_dword s6, s[6:7], 0x8
	s_mov_b32 s13, 1
	s_waitcnt lgkmcnt(0)
	s_mul_i32 s12, s5, s4
	s_mul_i32 s12, s12, s6
	s_branch .LBB0_1126
